# speedup vs baseline: 1.0020x; 1.0020x over previous
; template <int EPI, int AMAP, int KOFFMODE, int K>
; __device__ __forceinline__ void gemm_phase(unsigned char* smem, const bf16_t* A, int lda, const bf16_t* Bt, int NT, const EpiArgs& ea) {
;     ...
;         for (int kt = 0; kt < nk; ++kt) {
;             if (kt + 1 < nk) GEMM_DMA(m0, n0, kt + 1, cur ^ 1);
;             else if (have_next) GEMM_DMA(m0n, n0n, 0, cur ^ 1);
;             const unsigned char* Ac = smem + cur * STGB + (wm * 128 + l31) * 128;
;             const unsigned char* Bc = smem + cur * STGB + 32768 + (wn * 64 + l31) * 128;
;             bf16x8 fa[2][4], fb[2][2];
;             fb[0][0] = *(const bf16x8*)(Bc + (((0) ^ yz) & 7) * 16);
;             fb[0][1] = *(const bf16x8*)(Bc + 32 * 128 + (((0) ^ yz) & 7) * 16);
; #pragma unroll
;             for (int i = 0; i < 4; ++i) fa[0][i] = *(const bf16x8*)(Ac + i * 32 * 128 + (((0) ^ yz) & 7) * 16);
; #pragma unroll
;             for (int s = 0; s < 4; ++s) {
;                 if (s < 3) {
;                     const int o_ = (((2 * (s + 1)) ^ yz) & 7) * 16;
;                     fb[(s + 1) & 1][0] = *(const bf16x8*)(Bc + o_);
;                     fb[(s + 1) & 1][1] = *(const bf16x8*)(Bc + 32 * 128 + o_);
; #pragma unroll
;                     for (int i = 0; i < 4; ++i) fa[(s + 1) & 1][i] = *(const bf16x8*)(Ac + i * 32 * 128 + o_);
;                 }
; #pragma unroll
;                 for (int i = 0; i < 4; ++i) {
;                     acc[i][0] = __builtin_amdgcn_mfma_f32_32x32x16_bf16(fa[s & 1][i], fb[s & 1][0], acc[i][0], 0, 0, 0);
;                     acc[i][1] = __builtin_amdgcn_mfma_f32_32x32x16_bf16(fa[s & 1][i], fb[s & 1][1], acc[i][1], 0, 0, 0);
;                 }
;                 __builtin_amdgcn_sched_barrier(0);
;             }
;             if (kt + 1 < nk) asm volatile("s_waitcnt vmcnt(0)" ::: "memory");
;             __builtin_amdgcn_s_barrier();
;             cur ^= 1;
;         }
.LBB0_155:
	s_mov_b32 s9, s13
	s_lshl_b32 s13, s9, 16
	s_xor_b32 s12, s13, 0x10000
	v_readfirstlane_b32 s14, v142
	s_nop 0
	s_add_u32 s14, s14, s12
	v_add3_u32 v162, s13, v149, v147
	v_add_u32_e32 v162, v162, v151
	ds_read_b128 v[162:165], v162 offset:32768
	v_add3_u32 v208, s13, v149, v147
	v_add_u32_e32 v208, v208, v151
	ds_read_b128 v[208:211], v208 offset:36864
	s_waitcnt lgkmcnt(5)
	v_mfma_f32_32x32x16_bf16 v[114:129], v[192:195], v[154:157], v[114:129]
	v_mfma_f32_32x32x16_bf16 v[98:113], v[192:195], v[158:161], v[98:113]
	s_mov_b32 m0, s14
	v_lshl_add_u64 v[192:193], v[136:137], 0, s[4:5]
	v_lshl_add_u64 v[192:193], v[192:193], 0, s[20:21]
	global_load_lds_dwordx4 v[192:193], off
	s_add_u32 m0, s14, 0x2000
	v_lshl_add_u64 v[192:193], v[136:137], 0, s[4:5]
	v_lshl_add_u64 v[192:193], v[192:193], 0, s[80:81]
	global_load_lds_dwordx4 v[192:193], off
	v_add3_u32 v192, s13, v145, v147
	v_add_u32_e32 v192, v192, v151
	ds_read_b128 v[192:195], v192
	s_waitcnt lgkmcnt(5)
	v_mfma_f32_32x32x16_bf16 v[82:97], v[196:199], v[154:157], v[82:97]
	v_mfma_f32_32x32x16_bf16 v[66:81], v[196:199], v[158:161], v[66:81]
	s_add_u32 m0, s14, 0x4000
	v_lshl_add_u64 v[196:197], v[136:137], 0, s[4:5]
	v_lshl_add_u64 v[196:197], v[196:197], 0, s[88:89]
	global_load_lds_dwordx4 v[196:197], off
	s_add_u32 m0, s14, 0x6000
	v_lshl_add_u64 v[196:197], v[136:137], 0, s[4:5]
	v_lshl_add_u64 v[196:197], v[196:197], 0, s[62:63]
	global_load_lds_dwordx4 v[196:197], off
	v_add3_u32 v196, s13, v145, v147
	v_add_u32_e32 v196, v196, v151
	ds_read_b128 v[196:199], v196 offset:4096
	s_waitcnt lgkmcnt(5)
	v_mfma_f32_32x32x16_bf16 v[50:65], v[200:203], v[154:157], v[50:65]
	v_mfma_f32_32x32x16_bf16 v[34:49], v[200:203], v[158:161], v[34:49]
	s_add_u32 m0, s14, 0x8000
	v_lshl_add_u64 v[200:201], v[138:139], 0, s[4:5]
	v_lshl_add_u64 v[200:201], v[200:201], 0, vcc
	global_load_lds_dwordx4 v[200:201], off
	s_add_u32 m0, s14, 0xa000
	v_lshl_add_u64 v[200:201], v[138:139], 0, s[4:5]
	v_lshl_add_u64 v[200:201], v[200:201], 0, s[68:69]
	global_load_lds_dwordx4 v[200:201], off
	v_add3_u32 v200, s13, v145, v147
	v_add_u32_e32 v200, v200, v151
	ds_read_b128 v[200:203], v200 offset:8192
	s_waitcnt lgkmcnt(5)
	v_mfma_f32_32x32x16_bf16 v[18:33], v[204:207], v[154:157], v[18:33]
	v_mfma_f32_32x32x16_bf16 v[2:17], v[204:207], v[158:161], v[2:17]
	s_add_u32 m0, s14, 0xc000
	v_lshl_add_u64 v[204:205], v[138:139], 0, s[4:5]
	v_lshl_add_u64 v[204:205], v[204:205], 0, s[92:93]
	global_load_lds_dwordx4 v[204:205], off
	s_add_u32 m0, s14, 0xe000
	v_lshl_add_u64 v[204:205], v[138:139], 0, s[4:5]
	v_lshl_add_u64 v[204:205], v[204:205], 0, s[64:65]
	global_load_lds_dwordx4 v[204:205], off
	v_add3_u32 v204, s13, v145, v147
	v_add_u32_e32 v204, v204, v151
	ds_read_b128 v[204:207], v204 offset:12288
	v_add3_u32 v154, s13, v149, v147
	v_add_u32_e32 v154, v154, v152
	ds_read_b128 v[154:157], v154 offset:32768
	v_add3_u32 v158, s13, v149, v147
	v_add_u32_e32 v158, v158, v152
	ds_read_b128 v[158:161], v158 offset:36864
	s_waitcnt lgkmcnt(5)
	v_mfma_f32_32x32x16_bf16 v[114:129], v[192:195], v[162:165], v[114:129]
	v_mfma_f32_32x32x16_bf16 v[98:113], v[192:195], v[208:211], v[98:113]
	v_add3_u32 v192, s13, v145, v147
	v_add_u32_e32 v192, v192, v152
	ds_read_b128 v[192:195], v192
	s_waitcnt lgkmcnt(5)
	v_mfma_f32_32x32x16_bf16 v[82:97], v[196:199], v[162:165], v[82:97]
	v_mfma_f32_32x32x16_bf16 v[66:81], v[196:199], v[208:211], v[66:81]
	v_add3_u32 v196, s13, v145, v147
	v_add_u32_e32 v196, v196, v152
	ds_read_b128 v[196:199], v196 offset:4096
	s_waitcnt lgkmcnt(5)
	v_mfma_f32_32x32x16_bf16 v[50:65], v[200:203], v[162:165], v[50:65]
	v_mfma_f32_32x32x16_bf16 v[34:49], v[200:203], v[208:211], v[34:49]
	v_add3_u32 v200, s13, v145, v147
	v_add_u32_e32 v200, v200, v152
	ds_read_b128 v[200:203], v200 offset:8192
	s_waitcnt lgkmcnt(5)
	v_mfma_f32_32x32x16_bf16 v[18:33], v[204:207], v[162:165], v[18:33]
	v_mfma_f32_32x32x16_bf16 v[2:17], v[204:207], v[208:211], v[2:17]
	v_add3_u32 v204, s13, v145, v147
	v_add_u32_e32 v204, v204, v152
	ds_read_b128 v[204:207], v204 offset:12288
	v_add3_u32 v162, s13, v149, v147
	v_add_u32_e32 v162, v162, v153
	ds_read_b128 v[162:165], v162 offset:32768
	v_add3_u32 v208, s13, v149, v147
	v_add_u32_e32 v208, v208, v153
	ds_read_b128 v[208:211], v208 offset:36864
	s_waitcnt lgkmcnt(5)
	v_mfma_f32_32x32x16_bf16 v[114:129], v[192:195], v[154:157], v[114:129]
	v_mfma_f32_32x32x16_bf16 v[98:113], v[192:195], v[158:161], v[98:113]
	v_add3_u32 v192, s13, v145, v147
	v_add_u32_e32 v192, v192, v153
	ds_read_b128 v[192:195], v192
	s_waitcnt lgkmcnt(5)
	v_mfma_f32_32x32x16_bf16 v[82:97], v[196:199], v[154:157], v[82:97]
	v_mfma_f32_32x32x16_bf16 v[66:81], v[196:199], v[158:161], v[66:81]
	v_add3_u32 v196, s13, v145, v147
	v_add_u32_e32 v196, v196, v153
	ds_read_b128 v[196:199], v196 offset:4096
	s_waitcnt lgkmcnt(5)
	v_mfma_f32_32x32x16_bf16 v[50:65], v[200:203], v[154:157], v[50:65]
	v_mfma_f32_32x32x16_bf16 v[34:49], v[200:203], v[158:161], v[34:49]
	v_add3_u32 v200, s13, v145, v147
	v_add_u32_e32 v200, v200, v153
	ds_read_b128 v[200:203], v200 offset:8192
	s_waitcnt lgkmcnt(5)
	v_mfma_f32_32x32x16_bf16 v[18:33], v[204:207], v[154:157], v[18:33]
	v_mfma_f32_32x32x16_bf16 v[2:17], v[204:207], v[158:161], v[2:17]
	v_add3_u32 v204, s13, v145, v147
	v_add_u32_e32 v204, v204, v153
	ds_read_b128 v[204:207], v204 offset:12288
	s_waitcnt lgkmcnt(3)
	v_mfma_f32_32x32x16_bf16 v[114:129], v[192:195], v[162:165], v[114:129]
	v_mfma_f32_32x32x16_bf16 v[98:113], v[192:195], v[208:211], v[98:113]
	s_waitcnt lgkmcnt(2)
	v_mfma_f32_32x32x16_bf16 v[82:97], v[196:199], v[162:165], v[82:97]
	v_mfma_f32_32x32x16_bf16 v[66:81], v[196:199], v[208:211], v[66:81]
	s_waitcnt lgkmcnt(0)
	s_waitcnt vmcnt(0)
	s_barrier
; template <int EPI, int AMAP, int KOFFMODE, int K>
; __device__ __forceinline__ void gemm_phase(unsigned char* smem, const bf16_t* A, int lda, const bf16_t* Bt, int NT, const EpiArgs& ea) {
;     ...
;             for (int s = 0; s < 4; ++s) {
;                 if (s < 3) {
;                     const int o_ = (((2 * (s + 1)) ^ yz) & 7) * 16;
;                     fb[(s + 1) & 1][0] = *(const bf16x8*)(Bc + o_);
;                     fb[(s + 1) & 1][1] = *(const bf16x8*)(Bc + 32 * 128 + o_);
; #pragma unroll
;                     for (int i = 0; i < 4; ++i) fa[(s + 1) & 1][i] = *(const bf16x8*)(Ac + i * 32 * 128 + o_);
;                 }
; #pragma unroll
;                 for (int i = 0; i < 4; ++i) {
;                     acc[i][0] = __builtin_amdgcn_mfma_f32_32x32x16_bf16(fa[s & 1][i], fb[s & 1][0], acc[i][0], 0, 0, 0);
;                     acc[i][1] = __builtin_amdgcn_mfma_f32_32x32x16_bf16(fa[s & 1][i], fb[s & 1][1], acc[i][1], 0, 0, 0);
;                 }
;                 __builtin_amdgcn_sched_barrier(0);
;             }
;             if (kt + 1 < nk) asm volatile("s_waitcnt vmcnt(0)" ::: "memory");
;             __builtin_amdgcn_s_barrier();
;             cur ^= 1;
	v_add3_u32 v154, s12, v149, v147
	v_add_u32_e32 v154, v154, v150
	ds_read_b128 v[154:157], v154 offset:32768
	v_add3_u32 v158, s12, v149, v147
	v_add_u32_e32 v158, v158, v150
	ds_read_b128 v[158:161], v158 offset:36864
	v_add3_u32 v192, s12, v145, v147
	v_add_u32_e32 v192, v192, v150
	ds_read_b128 v[192:195], v192
	v_add3_u32 v196, s12, v145, v147
	v_add_u32_e32 v196, v196, v150
	ds_read_b128 v[196:199], v196 offset:4096
	v_mfma_f32_32x32x16_bf16 v[50:65], v[200:203], v[162:165], v[50:65]
	v_mfma_f32_32x32x16_bf16 v[34:49], v[200:203], v[208:211], v[34:49]
	v_add3_u32 v200, s12, v145, v147
	v_add_u32_e32 v200, v200, v150
	ds_read_b128 v[200:203], v200 offset:8192
	v_mfma_f32_32x32x16_bf16 v[18:33], v[204:207], v[162:165], v[18:33]
	v_mfma_f32_32x32x16_bf16 v[2:17], v[204:207], v[208:211], v[2:17]
	v_add3_u32 v204, s12, v145, v147
	v_add_u32_e32 v204, v204, v150
	ds_read_b128 v[204:207], v204 offset:12288
	s_xor_b32 s13, s9, 1
	s_add_u32 s4, s4, 0x80
	s_addc_u32 s5, s5, 0
	s_cmpk_eq_i32 s4, 0x780
	s_cbranch_scc0 .LBB0_155
	s_waitcnt lgkmcnt(0)
	s_andn2_b64 vcc, exec, s[2:3]
	s_lshl_b32 s2, s13, 16
	s_cbranch_vccnz .LBB0_147
	v_add_u32_e32 v136, s8, v141
	s_xor_b32 s3, s2, 0x10000
	v_ashrrev_i32_e32 v137, 31, v136
	v_add_u32_e32 v138, s7, v141
	v_add_u32_e32 v0, s3, v142
	v_lshlrev_b64 v[136:137], 11, v[136:137]
	v_ashrrev_i32_e32 v139, 31, v138
	v_add_u32_e32 v154, 0x8000, v0
	v_readfirstlane_b32 s3, v0
	v_lshlrev_b64 v[138:139], 11, v[138:139]
	v_lshl_add_u64 v[136:137], v[130:131], 0, v[136:137]
	s_mov_b32 m0, s3
	v_readfirstlane_b32 s3, v154
	v_add_u32_e32 v156, 0x2000, v0
	v_lshl_add_u64 v[138:139], v[132:133], 0, v[138:139]
	global_load_lds_dwordx4 v[136:137], off
	s_mov_b32 m0, s3
	s_mov_b64 s[4:5], 0x20000
	v_readfirstlane_b32 s3, v156
	v_add_u32_e32 v156, 0xa000, v0
	global_load_lds_dwordx4 v[138:139], off
	v_lshl_add_u64 v[154:155], v[136:137], 0, s[4:5]
	s_mov_b32 m0, s3
	v_readfirstlane_b32 s3, v156
	v_add_u32_e32 v156, 0x4000, v0
	global_load_lds_dwordx4 v[154:155], off
	v_lshl_add_u64 v[154:155], v[138:139], 0, s[4:5]
	s_mov_b32 m0, s3
	s_mov_b64 s[4:5], 0x40000
	v_readfirstlane_b32 s3, v156
	v_add_u32_e32 v156, 0xc000, v0
	global_load_lds_dwordx4 v[154:155], off
	v_lshl_add_u64 v[154:155], v[136:137], 0, s[4:5]
	s_mov_b32 m0, s3
	v_readfirstlane_b32 s3, v156
	global_load_lds_dwordx4 v[154:155], off
	v_lshl_add_u64 v[154:155], v[138:139], 0, s[4:5]
	s_mov_b32 m0, s3
	s_mov_b64 s[4:5], 0x60000
	global_load_lds_dwordx4 v[154:155], off
	v_add_u32_e32 v154, 0x6000, v0
	v_add_u32_e32 v0, 0xe000, v0
	v_readfirstlane_b32 s3, v154
	v_lshl_add_u64 v[136:137], v[136:137], 0, s[4:5]
	s_mov_b32 m0, s3
	v_readfirstlane_b32 s3, v0
	global_load_lds_dwordx4 v[136:137], off
	v_lshl_add_u64 v[136:137], v[138:139], 0, s[4:5]
	s_mov_b32 m0, s3
	s_nop 0
	global_load_lds_dwordx4 v[136:137], off
	s_branch .LBB0_147

; template <int EPI, int AMAP, int KOFFMODE, int K>
; __device__ __forceinline__ void gemm_phase(unsigned char* smem, const bf16_t* A, int lda, const bf16_t* Bt, int NT, const EpiArgs& ea) {
;     ...
;         for (int kt = 0; kt < nk; ++kt) {
;             if (kt + 1 < nk) GEMM_DMA(m0, n0, kt + 1, cur ^ 1);
;             else if (have_next) GEMM_DMA(m0n, n0n, 0, cur ^ 1);
;             const unsigned char* Ac = smem + cur * STGB + (wm * 128 + l31) * 128;
;             const unsigned char* Bc = smem + cur * STGB + 32768 + (wn * 64 + l31) * 128;
;             bf16x8 fa[2][4], fb[2][2];
;             fb[0][0] = *(const bf16x8*)(Bc + (((0) ^ yz) & 7) * 16);
;             fb[0][1] = *(const bf16x8*)(Bc + 32 * 128 + (((0) ^ yz) & 7) * 16);
; #pragma unroll
;             for (int i = 0; i < 4; ++i) fa[0][i] = *(const bf16x8*)(Ac + i * 32 * 128 + (((0) ^ yz) & 7) * 16);
; #pragma unroll
;             for (int s = 0; s < 4; ++s) {
;                 if (s < 3) {
;                     const int o_ = (((2 * (s + 1)) ^ yz) & 7) * 16;
;                     fb[(s + 1) & 1][0] = *(const bf16x8*)(Bc + o_);
;                     fb[(s + 1) & 1][1] = *(const bf16x8*)(Bc + 32 * 128 + o_);
; #pragma unroll
;                     for (int i = 0; i < 4; ++i) fa[(s + 1) & 1][i] = *(const bf16x8*)(Ac + i * 32 * 128 + o_);
;                 }
; #pragma unroll
;                 for (int i = 0; i < 4; ++i) {
;                     acc[i][0] = __builtin_amdgcn_mfma_f32_32x32x16_bf16(fa[s & 1][i], fb[s & 1][0], acc[i][0], 0, 0, 0);
;                     acc[i][1] = __builtin_amdgcn_mfma_f32_32x32x16_bf16(fa[s & 1][i], fb[s & 1][1], acc[i][1], 0, 0, 0);
;                 }
;                 __builtin_amdgcn_sched_barrier(0);
;             }
;             if (kt + 1 < nk) asm volatile("s_waitcnt vmcnt(0)" ::: "memory");
;             __builtin_amdgcn_s_barrier();
;             cur ^= 1;
;         }
.LBB0_461:
	s_mov_b32 s9, s13
	s_lshl_b32 s13, s9, 16
	s_xor_b32 s12, s13, 0x10000
	v_readfirstlane_b32 vcc_lo, v143
	s_nop 0
	s_add_u32 vcc_lo, vcc_lo, s12
	v_add3_u32 v155, s13, v150, v149
	v_add_u32_e32 v155, v155, v152
	v_add3_u32 v0, s13, v147, v149
	v_add_u32_e32 v0, v0, v152
	ds_read_b128 v[208:211], v155 offset:32768
	ds_read_b128 v[212:215], v155 offset:36864
	s_waitcnt lgkmcnt(5)
	v_mfma_f32_32x32x16_bf16 v[114:129], v[192:195], v[156:159], v[114:129]
	s_add_u32 s14, s4, 0xb240080
	s_addc_u32 s15, s5, 0
	s_mov_b32 m0, vcc_lo
	v_lshl_add_u64 v[164:165], v[136:137], 0, s[14:15]
	global_load_lds_dwordx4 v[164:165], off
	v_mfma_f32_32x32x16_bf16 v[98:113], v[192:195], v[160:163], v[98:113]
	s_add_u32 s14, s4, 0xb270080
	s_addc_u32 s15, s5, 0
	s_add_u32 m0, vcc_lo, 0x2000
	v_lshl_add_u64 v[164:165], v[136:137], 0, s[14:15]
	global_load_lds_dwordx4 v[164:165], off
	ds_read_b128 v[192:195], v0
	s_waitcnt lgkmcnt(5)
	v_mfma_f32_32x32x16_bf16 v[82:97], v[196:199], v[156:159], v[82:97]
	s_add_u32 s14, s4, 0xb2a0080
	s_addc_u32 s15, s5, 0
	s_add_u32 m0, vcc_lo, 0x4000
	v_lshl_add_u64 v[164:165], v[136:137], 0, s[14:15]
	global_load_lds_dwordx4 v[164:165], off
	v_mfma_f32_32x32x16_bf16 v[66:81], v[196:199], v[160:163], v[66:81]
	s_add_u32 s14, s4, 0xb2d0080
	s_addc_u32 s15, s5, 0
	s_add_u32 m0, vcc_lo, 0x6000
	v_lshl_add_u64 v[164:165], v[136:137], 0, s[14:15]
	global_load_lds_dwordx4 v[164:165], off
	ds_read_b128 v[196:199], v0 offset:4096
	s_waitcnt lgkmcnt(5)
	v_mfma_f32_32x32x16_bf16 v[50:65], v[200:203], v[156:159], v[50:65]
	v_mfma_f32_32x32x16_bf16 v[34:49], v[200:203], v[160:163], v[34:49]
	ds_read_b128 v[200:203], v0 offset:8192
	s_waitcnt lgkmcnt(5)
	v_mfma_f32_32x32x16_bf16 v[18:33], v[204:207], v[156:159], v[18:33]
	v_mfma_f32_32x32x16_bf16 v[2:17], v[204:207], v[160:163], v[2:17]
	ds_read_b128 v[204:207], v0 offset:12288
	v_add3_u32 v155, s13, v150, v149
	v_add_u32_e32 v155, v155, v153
	v_add3_u32 v0, s13, v147, v149
	v_add_u32_e32 v0, v0, v153
	ds_read_b128 v[156:159], v155 offset:32768
	ds_read_b128 v[160:163], v155 offset:36864
	s_waitcnt lgkmcnt(5)
	v_mfma_f32_32x32x16_bf16 v[114:129], v[192:195], v[208:211], v[114:129]
	v_mfma_f32_32x32x16_bf16 v[98:113], v[192:195], v[212:215], v[98:113]
	s_add_u32 s14, s4, 0xb00080
	s_addc_u32 s15, s5, 0
	s_add_u32 m0, vcc_lo, 0x8000
	v_lshl_add_u64 v[164:165], v[138:139], 0, s[14:15]
	global_load_lds_dwordx4 v[164:165], off
	ds_read_b128 v[192:195], v0
	s_waitcnt lgkmcnt(5)
	v_mfma_f32_32x32x16_bf16 v[82:97], v[196:199], v[208:211], v[82:97]
	v_mfma_f32_32x32x16_bf16 v[66:81], v[196:199], v[212:215], v[66:81]
	s_add_u32 s14, s4, 0xb30080
	s_addc_u32 s15, s5, 0
	s_add_u32 m0, vcc_lo, 0xa000
	v_lshl_add_u64 v[164:165], v[138:139], 0, s[14:15]
	global_load_lds_dwordx4 v[164:165], off
	ds_read_b128 v[196:199], v0 offset:4096
	s_waitcnt lgkmcnt(5)
	v_mfma_f32_32x32x16_bf16 v[50:65], v[200:203], v[208:211], v[50:65]
	v_mfma_f32_32x32x16_bf16 v[34:49], v[200:203], v[212:215], v[34:49]
	s_add_u32 s14, s4, 0xb60080
	s_addc_u32 s15, s5, 0
	s_add_u32 m0, vcc_lo, 0xc000
	v_lshl_add_u64 v[164:165], v[138:139], 0, s[14:15]
	global_load_lds_dwordx4 v[164:165], off
	ds_read_b128 v[200:203], v0 offset:8192
	s_waitcnt lgkmcnt(5)
	v_mfma_f32_32x32x16_bf16 v[18:33], v[204:207], v[208:211], v[18:33]
	v_mfma_f32_32x32x16_bf16 v[2:17], v[204:207], v[212:215], v[2:17]
	s_add_u32 s14, s4, 0xb90080
	s_addc_u32 s15, s5, 0
	s_add_u32 m0, vcc_lo, 0xe000
	v_lshl_add_u64 v[164:165], v[138:139], 0, s[14:15]
	global_load_lds_dwordx4 v[164:165], off
	ds_read_b128 v[204:207], v0 offset:12288
	v_add3_u32 v155, s13, v150, v149
	v_add_u32_e32 v155, v155, v154
	v_add3_u32 v0, s13, v147, v149
	v_add_u32_e32 v0, v0, v154
	ds_read_b128 v[208:211], v155 offset:32768
	ds_read_b128 v[212:215], v155 offset:36864
	s_waitcnt lgkmcnt(5)
	v_mfma_f32_32x32x16_bf16 v[114:129], v[192:195], v[156:159], v[114:129]
	v_mfma_f32_32x32x16_bf16 v[98:113], v[192:195], v[160:163], v[98:113]
	ds_read_b128 v[192:195], v0
	s_waitcnt lgkmcnt(5)
	v_mfma_f32_32x32x16_bf16 v[82:97], v[196:199], v[156:159], v[82:97]
	v_mfma_f32_32x32x16_bf16 v[66:81], v[196:199], v[160:163], v[66:81]
	ds_read_b128 v[196:199], v0 offset:4096
	s_waitcnt lgkmcnt(5)
	v_mfma_f32_32x32x16_bf16 v[50:65], v[200:203], v[156:159], v[50:65]
	v_mfma_f32_32x32x16_bf16 v[34:49], v[200:203], v[160:163], v[34:49]
	ds_read_b128 v[200:203], v0 offset:8192
	s_waitcnt lgkmcnt(5)
	v_mfma_f32_32x32x16_bf16 v[18:33], v[204:207], v[156:159], v[18:33]
	v_mfma_f32_32x32x16_bf16 v[2:17], v[204:207], v[160:163], v[2:17]
	ds_read_b128 v[204:207], v0 offset:12288
	s_waitcnt lgkmcnt(3)
	v_mfma_f32_32x32x16_bf16 v[114:129], v[192:195], v[208:211], v[114:129]
	v_mfma_f32_32x32x16_bf16 v[98:113], v[192:195], v[212:215], v[98:113]
	s_waitcnt lgkmcnt(2)
	v_mfma_f32_32x32x16_bf16 v[82:97], v[196:199], v[208:211], v[82:97]
	v_mfma_f32_32x32x16_bf16 v[66:81], v[196:199], v[212:215], v[66:81]
	s_waitcnt lgkmcnt(0)
	s_waitcnt vmcnt(0)
	s_barrier
; template <int EPI, int AMAP, int KOFFMODE, int K>
; __device__ __forceinline__ void gemm_phase(unsigned char* smem, const bf16_t* A, int lda, const bf16_t* Bt, int NT, const EpiArgs& ea) {
;     ...
;             for (int s = 0; s < 4; ++s) {
;                 if (s < 3) {
;                     const int o_ = (((2 * (s + 1)) ^ yz) & 7) * 16;
;                     fb[(s + 1) & 1][0] = *(const bf16x8*)(Bc + o_);
;                     fb[(s + 1) & 1][1] = *(const bf16x8*)(Bc + 32 * 128 + o_);
; #pragma unroll
;                     for (int i = 0; i < 4; ++i) fa[(s + 1) & 1][i] = *(const bf16x8*)(Ac + i * 32 * 128 + o_);
;                 }
; #pragma unroll
;                 for (int i = 0; i < 4; ++i) {
;                     acc[i][0] = __builtin_amdgcn_mfma_f32_32x32x16_bf16(fa[s & 1][i], fb[s & 1][0], acc[i][0], 0, 0, 0);
;                     acc[i][1] = __builtin_amdgcn_mfma_f32_32x32x16_bf16(fa[s & 1][i], fb[s & 1][1], acc[i][1], 0, 0, 0);
;                 }
;                 __builtin_amdgcn_sched_barrier(0);
;             }
;             if (kt + 1 < nk) asm volatile("s_waitcnt vmcnt(0)" ::: "memory");
;             __builtin_amdgcn_s_barrier();
;             cur ^= 1;
	v_add3_u32 v155, s12, v150, v149
	v_add_u32_e32 v155, v155, v151
	v_add3_u32 v0, s12, v147, v149
	v_add_u32_e32 v0, v0, v151
	ds_read_b128 v[156:159], v155 offset:32768
	ds_read_b128 v[160:163], v155 offset:36864
	ds_read_b128 v[192:195], v0
	ds_read_b128 v[196:199], v0 offset:4096
	v_mfma_f32_32x32x16_bf16 v[50:65], v[200:203], v[208:211], v[50:65]
	v_mfma_f32_32x32x16_bf16 v[34:49], v[200:203], v[212:215], v[34:49]
	ds_read_b128 v[200:203], v0 offset:8192
	v_mfma_f32_32x32x16_bf16 v[18:33], v[204:207], v[208:211], v[18:33]
	v_mfma_f32_32x32x16_bf16 v[2:17], v[204:207], v[212:215], v[2:17]
	ds_read_b128 v[204:207], v0 offset:12288
	s_xor_b32 s13, s9, 1
	s_add_u32 s4, s4, 0x80
	s_addc_u32 s5, s5, 0
	s_cmpk_eq_i32 s4, 0xb80
	s_cbranch_scc0 .LBB0_461
	s_waitcnt lgkmcnt(0)
	s_andn2_b64 vcc, exec, s[2:3]
	s_lshl_b32 s2, s13, 16
	s_cbranch_vccnz .LBB0_453
	v_add_u32_e32 v0, s8, v142
	s_xor_b32 s3, s2, 0x10000
	v_mad_i64_i32 v[138:139], s[4:5], v0, s37, v[130:131]
	v_add_u32_e32 v0, s3, v143
	v_add_u32_e32 v136, s7, v142
	v_add_u32_e32 v155, 0x8000, v0
	v_readfirstlane_b32 s3, v0
	v_mad_i64_i32 v[136:137], s[4:5], v136, s37, v[132:133]
	s_mov_b32 m0, s3
	v_readfirstlane_b32 s3, v155
	v_add_u32_e32 v155, 0x2000, v0
	global_load_lds_dwordx4 v[138:139], off
	s_mov_b32 m0, s3
	s_mov_b64 s[4:5], 0x30000
	v_readfirstlane_b32 s3, v155
	v_add_u32_e32 v155, 0xa000, v0
	global_load_lds_dwordx4 v[136:137], off
	v_lshl_add_u64 v[156:157], v[138:139], 0, s[4:5]
	s_mov_b32 m0, s3
	v_readfirstlane_b32 s3, v155
	v_add_u32_e32 v155, 0x4000, v0
	global_load_lds_dwordx4 v[156:157], off
	v_lshl_add_u64 v[156:157], v[136:137], 0, s[4:5]
	s_mov_b32 m0, s3
	s_mov_b64 s[4:5], 0x60000
	v_readfirstlane_b32 s3, v155
	v_add_u32_e32 v155, 0xc000, v0
	global_load_lds_dwordx4 v[156:157], off
	v_lshl_add_u64 v[156:157], v[138:139], 0, s[4:5]
	s_mov_b32 m0, s3
	v_readfirstlane_b32 s3, v155
	v_add_u32_e32 v155, 0x6000, v0
	global_load_lds_dwordx4 v[156:157], off
	v_lshl_add_u64 v[156:157], v[136:137], 0, s[4:5]
	s_mov_b32 m0, s3
	s_mov_b64 s[4:5], 0x90000
	v_readfirstlane_b32 s3, v155
	v_add_u32_e32 v0, 0xe000, v0
	global_load_lds_dwordx4 v[156:157], off
	v_lshl_add_u64 v[138:139], v[138:139], 0, s[4:5]
	s_mov_b32 m0, s3
	v_readfirstlane_b32 s3, v0
	global_load_lds_dwordx4 v[138:139], off
	v_lshl_add_u64 v[136:137], v[136:137], 0, s[4:5]
	s_mov_b32 m0, s3
	s_nop 0
	global_load_lds_dwordx4 v[136:137], off
	s_branch .LBB0_453

; template <int EPI, int AMAP, int KOFFMODE, int K>
; __device__ __forceinline__ void gemm_phase(unsigned char* smem, const bf16_t* A, int lda, const bf16_t* Bt, int NT, const EpiArgs& ea) {
;     ...
;         for (int kt = 0; kt < nk; ++kt) {
;             if (kt + 1 < nk) GEMM_DMA(m0, n0, kt + 1, cur ^ 1);
;             else if (have_next) GEMM_DMA(m0n, n0n, 0, cur ^ 1);
;             const unsigned char* Ac = smem + cur * STGB + (wm * 128 + l31) * 128;
;             const unsigned char* Bc = smem + cur * STGB + 32768 + (wn * 64 + l31) * 128;
;             bf16x8 fa[2][4], fb[2][2];
;             fb[0][0] = *(const bf16x8*)(Bc + (((0) ^ yz) & 7) * 16);
;             fb[0][1] = *(const bf16x8*)(Bc + 32 * 128 + (((0) ^ yz) & 7) * 16);
; #pragma unroll
;             for (int i = 0; i < 4; ++i) fa[0][i] = *(const bf16x8*)(Ac + i * 32 * 128 + (((0) ^ yz) & 7) * 16);
; #pragma unroll
;             for (int s = 0; s < 4; ++s) {
;                 if (s < 3) {
;                     const int o_ = (((2 * (s + 1)) ^ yz) & 7) * 16;
;                     fb[(s + 1) & 1][0] = *(const bf16x8*)(Bc + o_);
;                     fb[(s + 1) & 1][1] = *(const bf16x8*)(Bc + 32 * 128 + o_);
; #pragma unroll
;                     for (int i = 0; i < 4; ++i) fa[(s + 1) & 1][i] = *(const bf16x8*)(Ac + i * 32 * 128 + o_);
;                 }
; #pragma unroll
;                 for (int i = 0; i < 4; ++i) {
;                     acc[i][0] = __builtin_amdgcn_mfma_f32_32x32x16_bf16(fa[s & 1][i], fb[s & 1][0], acc[i][0], 0, 0, 0);
;                     acc[i][1] = __builtin_amdgcn_mfma_f32_32x32x16_bf16(fa[s & 1][i], fb[s & 1][1], acc[i][1], 0, 0, 0);
;                 }
;                 __builtin_amdgcn_sched_barrier(0);
;             }
;             if (kt + 1 < nk) asm volatile("s_waitcnt vmcnt(0)" ::: "memory");
;             __builtin_amdgcn_s_barrier();
;             cur ^= 1;
;         }
.LBB0_520:
	s_mov_b32 s9, s13
	s_lshl_b32 s13, s9, 16
	s_xor_b32 s12, s13, 0x10000
	v_readfirstlane_b32 s14, v142
	s_nop 0
	s_add_u32 s14, s14, s12
	v_add3_u32 v162, s13, v149, v147
	v_add_u32_e32 v162, v162, v151
	ds_read_b128 v[162:165], v162 offset:32768
	v_add3_u32 v208, s13, v149, v147
	v_add_u32_e32 v208, v208, v151
	ds_read_b128 v[208:211], v208 offset:36864
	s_waitcnt lgkmcnt(5)
	v_mfma_f32_32x32x16_bf16 v[114:129], v[192:195], v[154:157], v[114:129]
	v_mfma_f32_32x32x16_bf16 v[82:97], v[192:195], v[158:161], v[82:97]
	s_mov_b32 m0, s14
	v_lshl_add_u64 v[192:193], v[136:137], 0, s[4:5]
	v_lshl_add_u64 v[192:193], v[192:193], 0, s[20:21]
	global_load_lds_dwordx4 v[192:193], off
	s_add_u32 m0, s14, 0x2000
	v_lshl_add_u64 v[192:193], v[136:137], 0, s[4:5]
	v_lshl_add_u64 v[192:193], v[192:193], 0, s[80:81]
	global_load_lds_dwordx4 v[192:193], off
	v_add3_u32 v192, s13, v145, v147
	v_add_u32_e32 v192, v192, v151
	ds_read_b128 v[192:195], v192
	s_waitcnt lgkmcnt(5)
	v_mfma_f32_32x32x16_bf16 v[98:113], v[196:199], v[154:157], v[98:113]
	v_mfma_f32_32x32x16_bf16 v[66:81], v[196:199], v[158:161], v[66:81]
	s_add_u32 m0, s14, 0x4000
	v_lshl_add_u64 v[196:197], v[136:137], 0, s[4:5]
	v_lshl_add_u64 v[196:197], v[196:197], 0, s[88:89]
	global_load_lds_dwordx4 v[196:197], off
	s_add_u32 m0, s14, 0x6000
	v_lshl_add_u64 v[196:197], v[136:137], 0, s[4:5]
	v_lshl_add_u64 v[196:197], v[196:197], 0, s[62:63]
	global_load_lds_dwordx4 v[196:197], off
	v_add3_u32 v196, s13, v145, v147
	v_add_u32_e32 v196, v196, v151
	ds_read_b128 v[196:199], v196 offset:4096
	s_waitcnt lgkmcnt(5)
	v_mfma_f32_32x32x16_bf16 v[50:65], v[200:203], v[154:157], v[50:65]
	v_mfma_f32_32x32x16_bf16 v[18:33], v[200:203], v[158:161], v[18:33]
	s_add_u32 m0, s14, 0x8000
	v_lshl_add_u64 v[200:201], v[138:139], 0, s[4:5]
	v_lshl_add_u64 v[200:201], v[200:201], 0, vcc
	global_load_lds_dwordx4 v[200:201], off
	s_add_u32 m0, s14, 0xa000
	v_lshl_add_u64 v[200:201], v[138:139], 0, s[4:5]
	v_lshl_add_u64 v[200:201], v[200:201], 0, s[68:69]
	global_load_lds_dwordx4 v[200:201], off
	v_add3_u32 v200, s13, v145, v147
	v_add_u32_e32 v200, v200, v151
	ds_read_b128 v[200:203], v200 offset:8192
	s_waitcnt lgkmcnt(5)
	v_mfma_f32_32x32x16_bf16 v[34:49], v[204:207], v[154:157], v[34:49]
	v_mfma_f32_32x32x16_bf16 v[2:17], v[204:207], v[158:161], v[2:17]
	s_add_u32 m0, s14, 0xc000
	v_lshl_add_u64 v[204:205], v[138:139], 0, s[4:5]
	v_lshl_add_u64 v[204:205], v[204:205], 0, s[92:93]
	global_load_lds_dwordx4 v[204:205], off
	s_add_u32 m0, s14, 0xe000
	v_lshl_add_u64 v[204:205], v[138:139], 0, s[4:5]
	v_lshl_add_u64 v[204:205], v[204:205], 0, s[64:65]
	global_load_lds_dwordx4 v[204:205], off
	v_add3_u32 v204, s13, v145, v147
	v_add_u32_e32 v204, v204, v151
	ds_read_b128 v[204:207], v204 offset:12288
	v_add3_u32 v154, s13, v149, v147
	v_add_u32_e32 v154, v154, v152
	ds_read_b128 v[154:157], v154 offset:32768
	v_add3_u32 v158, s13, v149, v147
	v_add_u32_e32 v158, v158, v152
	ds_read_b128 v[158:161], v158 offset:36864
	s_waitcnt lgkmcnt(5)
	v_mfma_f32_32x32x16_bf16 v[114:129], v[192:195], v[162:165], v[114:129]
	v_mfma_f32_32x32x16_bf16 v[82:97], v[192:195], v[208:211], v[82:97]
	v_add3_u32 v192, s13, v145, v147
	v_add_u32_e32 v192, v192, v152
	ds_read_b128 v[192:195], v192
	s_waitcnt lgkmcnt(5)
	v_mfma_f32_32x32x16_bf16 v[98:113], v[196:199], v[162:165], v[98:113]
	v_mfma_f32_32x32x16_bf16 v[66:81], v[196:199], v[208:211], v[66:81]
	v_add3_u32 v196, s13, v145, v147
	v_add_u32_e32 v196, v196, v152
	ds_read_b128 v[196:199], v196 offset:4096
	s_waitcnt lgkmcnt(5)
	v_mfma_f32_32x32x16_bf16 v[50:65], v[200:203], v[162:165], v[50:65]
	v_mfma_f32_32x32x16_bf16 v[18:33], v[200:203], v[208:211], v[18:33]
	v_add3_u32 v200, s13, v145, v147
	v_add_u32_e32 v200, v200, v152
	ds_read_b128 v[200:203], v200 offset:8192
	s_waitcnt lgkmcnt(5)
	v_mfma_f32_32x32x16_bf16 v[34:49], v[204:207], v[162:165], v[34:49]
	v_mfma_f32_32x32x16_bf16 v[2:17], v[204:207], v[208:211], v[2:17]
	v_add3_u32 v204, s13, v145, v147
	v_add_u32_e32 v204, v204, v152
	ds_read_b128 v[204:207], v204 offset:12288
	v_add3_u32 v162, s13, v149, v147
	v_add_u32_e32 v162, v162, v153
	ds_read_b128 v[162:165], v162 offset:32768
	v_add3_u32 v208, s13, v149, v147
	v_add_u32_e32 v208, v208, v153
	ds_read_b128 v[208:211], v208 offset:36864
	s_waitcnt lgkmcnt(5)
	v_mfma_f32_32x32x16_bf16 v[114:129], v[192:195], v[154:157], v[114:129]
	v_mfma_f32_32x32x16_bf16 v[82:97], v[192:195], v[158:161], v[82:97]
	v_add3_u32 v192, s13, v145, v147
	v_add_u32_e32 v192, v192, v153
	ds_read_b128 v[192:195], v192
	s_waitcnt lgkmcnt(5)
	v_mfma_f32_32x32x16_bf16 v[98:113], v[196:199], v[154:157], v[98:113]
	v_mfma_f32_32x32x16_bf16 v[66:81], v[196:199], v[158:161], v[66:81]
	v_add3_u32 v196, s13, v145, v147
	v_add_u32_e32 v196, v196, v153
	ds_read_b128 v[196:199], v196 offset:4096
	s_waitcnt lgkmcnt(5)
	v_mfma_f32_32x32x16_bf16 v[50:65], v[200:203], v[154:157], v[50:65]
	v_mfma_f32_32x32x16_bf16 v[18:33], v[200:203], v[158:161], v[18:33]
	v_add3_u32 v200, s13, v145, v147
	v_add_u32_e32 v200, v200, v153
	ds_read_b128 v[200:203], v200 offset:8192
	s_waitcnt lgkmcnt(5)
	v_mfma_f32_32x32x16_bf16 v[34:49], v[204:207], v[154:157], v[34:49]
	v_mfma_f32_32x32x16_bf16 v[2:17], v[204:207], v[158:161], v[2:17]
	v_add3_u32 v204, s13, v145, v147
	v_add_u32_e32 v204, v204, v153
	ds_read_b128 v[204:207], v204 offset:12288
	s_waitcnt lgkmcnt(3)
	v_mfma_f32_32x32x16_bf16 v[114:129], v[192:195], v[162:165], v[114:129]
	v_mfma_f32_32x32x16_bf16 v[82:97], v[192:195], v[208:211], v[82:97]
	s_waitcnt lgkmcnt(2)
	v_mfma_f32_32x32x16_bf16 v[98:113], v[196:199], v[162:165], v[98:113]
	v_mfma_f32_32x32x16_bf16 v[66:81], v[196:199], v[208:211], v[66:81]
	s_waitcnt lgkmcnt(0)
	s_waitcnt vmcnt(0)
	s_barrier
; template <int EPI, int AMAP, int KOFFMODE, int K>
; __device__ __forceinline__ void gemm_phase(unsigned char* smem, const bf16_t* A, int lda, const bf16_t* Bt, int NT, const EpiArgs& ea) {
;     ...
;             for (int s = 0; s < 4; ++s) {
;                 if (s < 3) {
;                     const int o_ = (((2 * (s + 1)) ^ yz) & 7) * 16;
;                     fb[(s + 1) & 1][0] = *(const bf16x8*)(Bc + o_);
;                     fb[(s + 1) & 1][1] = *(const bf16x8*)(Bc + 32 * 128 + o_);
; #pragma unroll
;                     for (int i = 0; i < 4; ++i) fa[(s + 1) & 1][i] = *(const bf16x8*)(Ac + i * 32 * 128 + o_);
;                 }
; #pragma unroll
;                 for (int i = 0; i < 4; ++i) {
;                     acc[i][0] = __builtin_amdgcn_mfma_f32_32x32x16_bf16(fa[s & 1][i], fb[s & 1][0], acc[i][0], 0, 0, 0);
;                     acc[i][1] = __builtin_amdgcn_mfma_f32_32x32x16_bf16(fa[s & 1][i], fb[s & 1][1], acc[i][1], 0, 0, 0);
;                 }
;                 __builtin_amdgcn_sched_barrier(0);
;             }
;             if (kt + 1 < nk) asm volatile("s_waitcnt vmcnt(0)" ::: "memory");
;             __builtin_amdgcn_s_barrier();
;             cur ^= 1;
	v_add3_u32 v154, s12, v149, v147
	v_add_u32_e32 v154, v154, v150
	ds_read_b128 v[154:157], v154 offset:32768
	v_add3_u32 v158, s12, v149, v147
	v_add_u32_e32 v158, v158, v150
	ds_read_b128 v[158:161], v158 offset:36864
	v_add3_u32 v192, s12, v145, v147
	v_add_u32_e32 v192, v192, v150
	ds_read_b128 v[192:195], v192
	v_add3_u32 v196, s12, v145, v147
	v_add_u32_e32 v196, v196, v150
	ds_read_b128 v[196:199], v196 offset:4096
	v_mfma_f32_32x32x16_bf16 v[50:65], v[200:203], v[162:165], v[50:65]
	v_mfma_f32_32x32x16_bf16 v[18:33], v[200:203], v[208:211], v[18:33]
	v_add3_u32 v200, s12, v145, v147
	v_add_u32_e32 v200, v200, v150
	ds_read_b128 v[200:203], v200 offset:8192
	v_mfma_f32_32x32x16_bf16 v[34:49], v[204:207], v[162:165], v[34:49]
	v_mfma_f32_32x32x16_bf16 v[2:17], v[204:207], v[208:211], v[2:17]
	v_add3_u32 v204, s12, v145, v147
	v_add_u32_e32 v204, v204, v150
	ds_read_b128 v[204:207], v204 offset:12288
	s_xor_b32 s13, s9, 1
	s_add_u32 s4, s4, 0x80
	s_addc_u32 s5, s5, 0
	s_cmpk_eq_i32 s4, 0x780
	s_cbranch_scc0 .LBB0_520
	s_waitcnt lgkmcnt(0)
	s_andn2_b64 vcc, exec, s[2:3]
	s_lshl_b32 s2, s13, 16
	s_mov_b64 s[62:63], 0x80
	s_mov_b64 s[64:65], 0x10000
	s_mov_b32 s92, 0x3e38aa3b
	s_cbranch_vccnz .LBB0_523
	v_add_u32_e32 v136, s8, v141
	s_xor_b32 s3, s2, 0x10000
	v_ashrrev_i32_e32 v137, 31, v136
	v_add_u32_e32 v138, s7, v141
	v_add_u32_e32 v0, s3, v142
	v_lshlrev_b64 v[136:137], 11, v[136:137]
	v_ashrrev_i32_e32 v139, 31, v138
	v_add_u32_e32 v154, 0x8000, v0
	v_readfirstlane_b32 s3, v0
	v_lshlrev_b64 v[138:139], 11, v[138:139]
	v_lshl_add_u64 v[136:137], v[130:131], 0, v[136:137]
	s_mov_b32 m0, s3
	v_readfirstlane_b32 s3, v154
	v_add_u32_e32 v156, 0x2000, v0
	v_lshl_add_u64 v[138:139], v[132:133], 0, v[138:139]
	global_load_lds_dwordx4 v[136:137], off
	s_mov_b32 m0, s3
	s_mov_b64 s[4:5], 0x20000
	v_readfirstlane_b32 s3, v156
	v_add_u32_e32 v156, 0xa000, v0
	global_load_lds_dwordx4 v[138:139], off
	v_lshl_add_u64 v[154:155], v[136:137], 0, s[4:5]
	s_mov_b32 m0, s3
	v_readfirstlane_b32 s3, v156
	v_add_u32_e32 v156, 0x4000, v0
	global_load_lds_dwordx4 v[154:155], off
	v_lshl_add_u64 v[154:155], v[138:139], 0, s[4:5]
	s_mov_b32 m0, s3
	s_mov_b64 s[4:5], 0x40000
	v_readfirstlane_b32 s3, v156
	v_add_u32_e32 v156, 0xc000, v0
	global_load_lds_dwordx4 v[154:155], off
	v_lshl_add_u64 v[154:155], v[136:137], 0, s[4:5]
	s_mov_b32 m0, s3
	v_readfirstlane_b32 s3, v156
	global_load_lds_dwordx4 v[154:155], off
	v_lshl_add_u64 v[154:155], v[138:139], 0, s[4:5]
	s_mov_b32 m0, s3
	s_mov_b64 s[4:5], 0x60000
	global_load_lds_dwordx4 v[154:155], off
	v_add_u32_e32 v154, 0x6000, v0
	v_add_u32_e32 v0, 0xe000, v0
	v_readfirstlane_b32 s3, v154
	v_lshl_add_u64 v[136:137], v[136:137], 0, s[4:5]
	s_mov_b32 m0, s3
	v_readfirstlane_b32 s3, v0
	global_load_lds_dwordx4 v[136:137], off
	v_lshl_add_u64 v[136:137], v[138:139], 0, s[4:5]
	s_mov_b32 m0, s3
	s_nop 0
	global_load_lds_dwordx4 v[136:137], off

; template <int EPI, int AMAP, int KOFFMODE, int K>
; __device__ __forceinline__ void gemm_phase(unsigned char* smem, const bf16_t* A, int lda, const bf16_t* Bt, int NT, const EpiArgs& ea) {
;     ...
;         for (int kt = 0; kt < nk; ++kt) {
;             if (kt + 1 < nk) GEMM_DMA(m0, n0, kt + 1, cur ^ 1);
;             else if (have_next) GEMM_DMA(m0n, n0n, 0, cur ^ 1);
;             const unsigned char* Ac = smem + cur * STGB + (wm * 128 + l31) * 128;
;             const unsigned char* Bc = smem + cur * STGB + 32768 + (wn * 64 + l31) * 128;
;             bf16x8 fa[2][4], fb[2][2];
;             fb[0][0] = *(const bf16x8*)(Bc + (((0) ^ yz) & 7) * 16);
;             fb[0][1] = *(const bf16x8*)(Bc + 32 * 128 + (((0) ^ yz) & 7) * 16);
; #pragma unroll
;             for (int i = 0; i < 4; ++i) fa[0][i] = *(const bf16x8*)(Ac + i * 32 * 128 + (((0) ^ yz) & 7) * 16);
; #pragma unroll
;             for (int s = 0; s < 4; ++s) {
;                 if (s < 3) {
;                     const int o_ = (((2 * (s + 1)) ^ yz) & 7) * 16;
;                     fb[(s + 1) & 1][0] = *(const bf16x8*)(Bc + o_);
;                     fb[(s + 1) & 1][1] = *(const bf16x8*)(Bc + 32 * 128 + o_);
; #pragma unroll
;                     for (int i = 0; i < 4; ++i) fa[(s + 1) & 1][i] = *(const bf16x8*)(Ac + i * 32 * 128 + o_);
;                 }
; #pragma unroll
;                 for (int i = 0; i < 4; ++i) {
;                     acc[i][0] = __builtin_amdgcn_mfma_f32_32x32x16_bf16(fa[s & 1][i], fb[s & 1][0], acc[i][0], 0, 0, 0);
;                     acc[i][1] = __builtin_amdgcn_mfma_f32_32x32x16_bf16(fa[s & 1][i], fb[s & 1][1], acc[i][1], 0, 0, 0);
;                 }
;                 __builtin_amdgcn_sched_barrier(0);
;             }
;             if (kt + 1 < nk) asm volatile("s_waitcnt vmcnt(0)" ::: "memory");
;             __builtin_amdgcn_s_barrier();
;             cur ^= 1;
;         }
.LBB0_927:
	s_lshr_b32 s14, s12, 1
	s_mulk_i32 s14, 0xc0
	s_and_b32 s20, s13, 64
	s_add_i32 s20, s14, s20
	s_mov_b32 s9, s15
	s_lshl_b32 s15, s9, 16
	s_xor_b32 s14, s15, 0x10000
	v_readfirstlane_b32 s28, v143
	s_nop 0
	s_add_u32 s28, s28, s14
	v_add3_u32 v155, s15, v150, v149
	v_add_u32_e32 v155, v155, v152
	v_add3_u32 v0, s15, v147, v149
	v_add_u32_e32 v0, v0, v152
	ds_read_b128 v[208:211], v155 offset:32768
	ds_read_b128 v[212:215], v155 offset:36864
	s_waitcnt lgkmcnt(5)
	v_mfma_f32_32x32x16_bf16 v[114:129], v[192:195], v[156:159], v[114:129]
	s_lshl_b64 s[34:35], s[20:21], 1
	s_mov_b32 m0, s28
	v_lshl_add_u64 v[164:165], v[136:137], 0, s[34:35]
	global_load_lds_dwordx4 v[164:165], off
	v_mfma_f32_32x32x16_bf16 v[98:113], v[192:195], v[160:163], v[98:113]
	s_lshl_b64 s[34:35], s[20:21], 1
	s_add_u32 s34, s34, 0x60000
	s_addc_u32 s35, s35, 0
	s_add_u32 m0, s28, 0x2000
	v_lshl_add_u64 v[164:165], v[136:137], 0, s[34:35]
	global_load_lds_dwordx4 v[164:165], off
	ds_read_b128 v[192:195], v0
	s_waitcnt lgkmcnt(5)
	v_mfma_f32_32x32x16_bf16 v[82:97], v[196:199], v[156:159], v[82:97]
	s_lshl_b64 s[34:35], s[20:21], 1
	s_add_u32 s34, s34, 0xc0000
	s_addc_u32 s35, s35, 0
	s_add_u32 m0, s28, 0x4000
	v_lshl_add_u64 v[164:165], v[136:137], 0, s[34:35]
	global_load_lds_dwordx4 v[164:165], off
	v_mfma_f32_32x32x16_bf16 v[66:81], v[196:199], v[160:163], v[66:81]
	s_lshl_b64 s[34:35], s[20:21], 1
	s_add_u32 s34, s34, 0x120000
	s_addc_u32 s35, s35, 0
	s_add_u32 m0, s28, 0x6000
	v_lshl_add_u64 v[164:165], v[136:137], 0, s[34:35]
	global_load_lds_dwordx4 v[164:165], off
	ds_read_b128 v[196:199], v0 offset:4096
	s_waitcnt lgkmcnt(5)
	v_mfma_f32_32x32x16_bf16 v[50:65], v[200:203], v[156:159], v[50:65]
	v_mfma_f32_32x32x16_bf16 v[34:49], v[200:203], v[160:163], v[34:49]
	ds_read_b128 v[200:203], v0 offset:8192
	s_waitcnt lgkmcnt(5)
	v_mfma_f32_32x32x16_bf16 v[18:33], v[204:207], v[156:159], v[18:33]
	v_mfma_f32_32x32x16_bf16 v[2:17], v[204:207], v[160:163], v[2:17]
	ds_read_b128 v[204:207], v0 offset:12288
	v_add3_u32 v155, s15, v150, v149
	v_add_u32_e32 v155, v155, v153
	v_add3_u32 v0, s15, v147, v149
	v_add_u32_e32 v0, v0, v153
	ds_read_b128 v[156:159], v155 offset:32768
	ds_read_b128 v[160:163], v155 offset:36864
	s_waitcnt lgkmcnt(5)
	v_mfma_f32_32x32x16_bf16 v[114:129], v[192:195], v[208:211], v[114:129]
	v_mfma_f32_32x32x16_bf16 v[98:113], v[192:195], v[212:215], v[98:113]
	s_add_u32 s34, s4, 0x7c0080
	s_addc_u32 s35, s5, 0
	s_add_u32 m0, s28, 0x8000
	v_lshl_add_u64 v[164:165], v[138:139], 0, s[34:35]
	global_load_lds_dwordx4 v[164:165], off
	ds_read_b128 v[192:195], v0
	s_waitcnt lgkmcnt(5)
	v_mfma_f32_32x32x16_bf16 v[82:97], v[196:199], v[208:211], v[82:97]
	v_mfma_f32_32x32x16_bf16 v[66:81], v[196:199], v[212:215], v[66:81]
	s_add_u32 s34, s4, s68
	s_addc_u32 s35, s5, s69
	s_add_u32 m0, s28, 0xa000
	v_lshl_add_u64 v[164:165], v[138:139], 0, s[34:35]
	global_load_lds_dwordx4 v[164:165], off
	ds_read_b128 v[196:199], v0 offset:4096
	s_waitcnt lgkmcnt(5)
	v_mfma_f32_32x32x16_bf16 v[50:65], v[200:203], v[208:211], v[50:65]
	v_mfma_f32_32x32x16_bf16 v[34:49], v[200:203], v[212:215], v[34:49]
	s_add_u32 s34, s4, s80
	s_addc_u32 s35, s5, s81
	s_add_u32 m0, s28, 0xc000
	v_lshl_add_u64 v[164:165], v[138:139], 0, s[34:35]
	global_load_lds_dwordx4 v[164:165], off
	ds_read_b128 v[200:203], v0 offset:8192
	s_waitcnt lgkmcnt(5)
	v_mfma_f32_32x32x16_bf16 v[18:33], v[204:207], v[208:211], v[18:33]
	v_mfma_f32_32x32x16_bf16 v[2:17], v[204:207], v[212:215], v[2:17]
	s_add_u32 s34, s4, 0x880080
	s_addc_u32 s35, s5, 0
	s_add_u32 m0, s28, 0xe000
	v_lshl_add_u64 v[164:165], v[138:139], 0, s[34:35]
	global_load_lds_dwordx4 v[164:165], off
	ds_read_b128 v[204:207], v0 offset:12288
	v_add3_u32 v155, s15, v150, v149
	v_add_u32_e32 v155, v155, v154
	v_add3_u32 v0, s15, v147, v149
	v_add_u32_e32 v0, v0, v154
	ds_read_b128 v[208:211], v155 offset:32768
	ds_read_b128 v[212:215], v155 offset:36864
	s_waitcnt lgkmcnt(5)
	v_mfma_f32_32x32x16_bf16 v[114:129], v[192:195], v[156:159], v[114:129]
	v_mfma_f32_32x32x16_bf16 v[98:113], v[192:195], v[160:163], v[98:113]
	ds_read_b128 v[192:195], v0
	s_waitcnt lgkmcnt(5)
	v_mfma_f32_32x32x16_bf16 v[82:97], v[196:199], v[156:159], v[82:97]
	v_mfma_f32_32x32x16_bf16 v[66:81], v[196:199], v[160:163], v[66:81]
	ds_read_b128 v[196:199], v0 offset:4096
	s_waitcnt lgkmcnt(5)
	v_mfma_f32_32x32x16_bf16 v[50:65], v[200:203], v[156:159], v[50:65]
	v_mfma_f32_32x32x16_bf16 v[34:49], v[200:203], v[160:163], v[34:49]
	ds_read_b128 v[200:203], v0 offset:8192
	s_waitcnt lgkmcnt(5)
	v_mfma_f32_32x32x16_bf16 v[18:33], v[204:207], v[156:159], v[18:33]
	v_mfma_f32_32x32x16_bf16 v[2:17], v[204:207], v[160:163], v[2:17]
	ds_read_b128 v[204:207], v0 offset:12288
	s_waitcnt lgkmcnt(3)
	v_mfma_f32_32x32x16_bf16 v[114:129], v[192:195], v[208:211], v[114:129]
	v_mfma_f32_32x32x16_bf16 v[98:113], v[192:195], v[212:215], v[98:113]
	s_waitcnt lgkmcnt(2)
	v_mfma_f32_32x32x16_bf16 v[82:97], v[196:199], v[208:211], v[82:97]
	v_mfma_f32_32x32x16_bf16 v[66:81], v[196:199], v[212:215], v[66:81]
	s_waitcnt lgkmcnt(0)
	s_waitcnt vmcnt(0)
	s_barrier
; template <int EPI, int AMAP, int KOFFMODE, int K>
; __device__ __forceinline__ void gemm_phase(unsigned char* smem, const bf16_t* A, int lda, const bf16_t* Bt, int NT, const EpiArgs& ea) {
;     ...
;             for (int s = 0; s < 4; ++s) {
;                 if (s < 3) {
;                     const int o_ = (((2 * (s + 1)) ^ yz) & 7) * 16;
;                     fb[(s + 1) & 1][0] = *(const bf16x8*)(Bc + o_);
;                     fb[(s + 1) & 1][1] = *(const bf16x8*)(Bc + 32 * 128 + o_);
; #pragma unroll
;                     for (int i = 0; i < 4; ++i) fa[(s + 1) & 1][i] = *(const bf16x8*)(Ac + i * 32 * 128 + o_);
;                 }
; #pragma unroll
;                 for (int i = 0; i < 4; ++i) {
;                     acc[i][0] = __builtin_amdgcn_mfma_f32_32x32x16_bf16(fa[s & 1][i], fb[s & 1][0], acc[i][0], 0, 0, 0);
;                     acc[i][1] = __builtin_amdgcn_mfma_f32_32x32x16_bf16(fa[s & 1][i], fb[s & 1][1], acc[i][1], 0, 0, 0);
;                 }
;                 __builtin_amdgcn_sched_barrier(0);
;             }
;             if (kt + 1 < nk) asm volatile("s_waitcnt vmcnt(0)" ::: "memory");
;             __builtin_amdgcn_s_barrier();
;             cur ^= 1;
	v_add3_u32 v155, s14, v150, v149
	v_add_u32_e32 v155, v155, v151
	v_add3_u32 v0, s14, v147, v149
	v_add_u32_e32 v0, v0, v151
	ds_read_b128 v[156:159], v155 offset:32768
	ds_read_b128 v[160:163], v155 offset:36864
	ds_read_b128 v[192:195], v0
	ds_read_b128 v[196:199], v0 offset:4096
	v_mfma_f32_32x32x16_bf16 v[50:65], v[200:203], v[208:211], v[50:65]
	v_mfma_f32_32x32x16_bf16 v[34:49], v[200:203], v[212:215], v[34:49]
	ds_read_b128 v[200:203], v0 offset:8192
	v_mfma_f32_32x32x16_bf16 v[18:33], v[204:207], v[208:211], v[18:33]
	v_mfma_f32_32x32x16_bf16 v[2:17], v[204:207], v[212:215], v[2:17]
	ds_read_b128 v[204:207], v0 offset:12288
	s_xor_b32 s15, s9, 1
	s_add_u32 s4, s4, 0x80
	s_addc_u32 s5, s5, 0
	s_add_i32 s12, s12, 1
	s_add_i32 s13, s13, 64
	s_mov_b64 s[34:35], 0x60000
	s_cmpk_eq_i32 s4, 0xf80
	s_cbranch_scc0 .LBB0_927
	s_waitcnt lgkmcnt(0)
	v_writelane_b32 v251, s20, 18
	s_andn2_b64 vcc, exec, s[2:3]
	s_lshl_b32 s2, s15, 16
	v_writelane_b32 v251, s21, 19
	s_cbranch_vccnz .LBB0_919
	v_add_u32_e32 v0, s8, v142
	s_movk_i32 s3, 0x1800
	v_mad_i64_i32 v[138:139], s[4:5], v0, s3, v[130:131]
	s_xor_b32 s3, s2, 0x10000
	v_add_u32_e32 v136, s7, v142
	v_add_u32_e32 v0, s3, v143
	v_ashrrev_i32_e32 v137, 31, v136
	v_add_u32_e32 v155, 0x8000, v0
	v_readfirstlane_b32 s3, v0
	v_lshlrev_b64 v[136:137], 12, v[136:137]
	s_mov_b32 m0, s3
	v_readfirstlane_b32 s3, v155
	v_add_u32_e32 v155, 0x2000, v0
	v_lshl_add_u64 v[136:137], v[132:133], 0, v[136:137]
	global_load_lds_dwordx4 v[138:139], off
	s_mov_b32 m0, s3
	v_readfirstlane_b32 s3, v155
	v_add_u32_e32 v155, 0xa000, v0
	global_load_lds_dwordx4 v[136:137], off
	v_lshl_add_u64 v[156:157], v[138:139], 0, s[34:35]
	s_mov_b32 m0, s3
	s_mov_b64 s[4:5], 0x40000
	v_readfirstlane_b32 s3, v155
	v_add_u32_e32 v155, 0x4000, v0
	global_load_lds_dwordx4 v[156:157], off
	v_lshl_add_u64 v[156:157], v[136:137], 0, s[4:5]
	s_mov_b32 m0, s3
	s_mov_b64 s[4:5], 0xc0000
	v_readfirstlane_b32 s3, v155
	v_add_u32_e32 v155, 0xc000, v0
	global_load_lds_dwordx4 v[156:157], off
	v_lshl_add_u64 v[156:157], v[138:139], 0, s[4:5]
	s_mov_b32 m0, s3
	s_mov_b64 s[12:13], 0x80000
	v_readfirstlane_b32 s3, v155
	v_add_u32_e32 v155, 0x6000, v0
	global_load_lds_dwordx4 v[156:157], off
	v_lshl_add_u64 v[156:157], v[136:137], 0, s[12:13]
	s_mov_b32 m0, s3
	s_mov_b64 s[12:13], 0x120000
	v_readfirstlane_b32 s3, v155
	v_add_u32_e32 v0, 0xe000, v0
	global_load_lds_dwordx4 v[156:157], off
	v_lshl_add_u64 v[138:139], v[138:139], 0, s[12:13]
	s_mov_b32 m0, s3
	v_readfirstlane_b32 s3, v0
	global_load_lds_dwordx4 v[138:139], off
	v_lshl_add_u64 v[136:137], v[136:137], 0, s[4:5]
	s_mov_b32 m0, s3
	s_nop 0
	global_load_lds_dwordx4 v[136:137], off
	s_branch .LBB0_919

; template <int EPI, int AMAP, int KOFFMODE, int K>
; __device__ __forceinline__ void gemm_phase(unsigned char* smem, const bf16_t* A, int lda, const bf16_t* Bt, int NT, const EpiArgs& ea) {
;     ...
;         for (int kt = 0; kt < nk; ++kt) {
;             if (kt + 1 < nk) GEMM_DMA(m0, n0, kt + 1, cur ^ 1);
;             else if (have_next) GEMM_DMA(m0n, n0n, 0, cur ^ 1);
;             const unsigned char* Ac = smem + cur * STGB + (wm * 128 + l31) * 128;
;             const unsigned char* Bc = smem + cur * STGB + 32768 + (wn * 64 + l31) * 128;
;             bf16x8 fa[2][4], fb[2][2];
;             fb[0][0] = *(const bf16x8*)(Bc + (((0) ^ yz) & 7) * 16);
;             fb[0][1] = *(const bf16x8*)(Bc + 32 * 128 + (((0) ^ yz) & 7) * 16);
; #pragma unroll
;             for (int i = 0; i < 4; ++i) fa[0][i] = *(const bf16x8*)(Ac + i * 32 * 128 + (((0) ^ yz) & 7) * 16);
; #pragma unroll
;             for (int s = 0; s < 4; ++s) {
;                 if (s < 3) {
;                     const int o_ = (((2 * (s + 1)) ^ yz) & 7) * 16;
;                     fb[(s + 1) & 1][0] = *(const bf16x8*)(Bc + o_);
;                     fb[(s + 1) & 1][1] = *(const bf16x8*)(Bc + 32 * 128 + o_);
; #pragma unroll
;                     for (int i = 0; i < 4; ++i) fa[(s + 1) & 1][i] = *(const bf16x8*)(Ac + i * 32 * 128 + o_);
;                 }
; #pragma unroll
;                 for (int i = 0; i < 4; ++i) {
;                     acc[i][0] = __builtin_amdgcn_mfma_f32_32x32x16_bf16(fa[s & 1][i], fb[s & 1][0], acc[i][0], 0, 0, 0);
;                     acc[i][1] = __builtin_amdgcn_mfma_f32_32x32x16_bf16(fa[s & 1][i], fb[s & 1][1], acc[i][1], 0, 0, 0);
;                 }
;                 __builtin_amdgcn_sched_barrier(0);
;             }
;             if (kt + 1 < nk) asm volatile("s_waitcnt vmcnt(0)" ::: "memory");
;             __builtin_amdgcn_s_barrier();
;             cur ^= 1;
;         }
.LBB0_1032:
	s_mov_b32 s11, s15
	s_lshl_b32 s15, s11, 16
	s_xor_b32 s14, s15, 0x10000
	v_readfirstlane_b32 s28, v144
	s_nop 0
	s_add_u32 s28, s28, s14
	v_add3_u32 v191, s15, v151, v150
	v_add_u32_e32 v191, v191, v153
	v_add3_u32 v0, s15, v149, v150
	v_add_u32_e32 v0, v0, v153
	ds_read_b128 v[208:211], v191 offset:32768
	ds_read_b128 v[212:215], v191 offset:36864
	s_waitcnt lgkmcnt(5)
	v_mfma_f32_32x32x16_bf16 v[114:129], v[192:195], v[156:159], v[114:129]
	s_add_u32 s34, s4, s20
	s_addc_u32 s35, s5, s21
	s_mov_b32 m0, s28
	v_lshl_add_u64 v[164:165], v[136:137], 0, s[34:35]
	global_load_lds_dwordx4 v[164:165], off
	v_mfma_f32_32x32x16_bf16 v[98:113], v[192:195], v[160:163], v[98:113]
	s_add_u32 s34, s4, vcc_lo
	s_addc_u32 s35, s5, vcc_hi
	s_add_u32 m0, s28, 0x2000
	v_lshl_add_u64 v[164:165], v[136:137], 0, s[34:35]
	global_load_lds_dwordx4 v[164:165], off
	ds_read_b128 v[192:195], v0
	s_waitcnt lgkmcnt(5)
	v_mfma_f32_32x32x16_bf16 v[82:97], v[196:199], v[156:159], v[82:97]
	s_add_u32 s34, s4, s68
	s_addc_u32 s35, s5, s69
	s_add_u32 m0, s28, 0x4000
	v_lshl_add_u64 v[164:165], v[136:137], 0, s[34:35]
	global_load_lds_dwordx4 v[164:165], off
	v_mfma_f32_32x32x16_bf16 v[66:81], v[196:199], v[160:163], v[66:81]
	s_add_u32 s34, s4, s88
	s_addc_u32 s35, s5, s89
	s_add_u32 m0, s28, 0x6000
	v_lshl_add_u64 v[164:165], v[136:137], 0, s[34:35]
	global_load_lds_dwordx4 v[164:165], off
	ds_read_b128 v[196:199], v0 offset:4096
	s_waitcnt lgkmcnt(5)
	v_mfma_f32_32x32x16_bf16 v[50:65], v[200:203], v[156:159], v[50:65]
	v_mfma_f32_32x32x16_bf16 v[34:49], v[200:203], v[160:163], v[34:49]
	ds_read_b128 v[200:203], v0 offset:8192
	s_waitcnt lgkmcnt(5)
	v_mfma_f32_32x32x16_bf16 v[18:33], v[204:207], v[156:159], v[18:33]
	v_mfma_f32_32x32x16_bf16 v[2:17], v[204:207], v[160:163], v[2:17]
	ds_read_b128 v[204:207], v0 offset:12288
	v_add3_u32 v191, s15, v151, v150
	v_add_u32_e32 v191, v191, v154
	v_add3_u32 v0, s15, v149, v150
	v_add_u32_e32 v0, v0, v154
	ds_read_b128 v[156:159], v191 offset:32768
	ds_read_b128 v[160:163], v191 offset:36864
	s_waitcnt lgkmcnt(5)
	v_mfma_f32_32x32x16_bf16 v[114:129], v[192:195], v[208:211], v[114:129]
	v_mfma_f32_32x32x16_bf16 v[98:113], v[192:195], v[212:215], v[98:113]
	s_add_u32 s34, s4, 0xe00080
	s_addc_u32 s35, s5, 0
	s_add_u32 m0, s28, 0x8000
	v_lshl_add_u64 v[164:165], v[138:139], 0, s[34:35]
	global_load_lds_dwordx4 v[164:165], off
	ds_read_b128 v[192:195], v0
	s_waitcnt lgkmcnt(5)
	v_mfma_f32_32x32x16_bf16 v[82:97], v[196:199], v[208:211], v[82:97]
	v_mfma_f32_32x32x16_bf16 v[66:81], v[196:199], v[212:215], v[66:81]
	s_add_u32 s34, s4, 0xe20080
	s_addc_u32 s35, s5, 0
	s_add_u32 m0, s28, 0xa000
	v_lshl_add_u64 v[164:165], v[138:139], 0, s[34:35]
	global_load_lds_dwordx4 v[164:165], off
	ds_read_b128 v[196:199], v0 offset:4096
	s_waitcnt lgkmcnt(5)
	v_mfma_f32_32x32x16_bf16 v[50:65], v[200:203], v[208:211], v[50:65]
	v_mfma_f32_32x32x16_bf16 v[34:49], v[200:203], v[212:215], v[34:49]
	s_add_u32 s34, s4, 0xe40080
	s_addc_u32 s35, s5, 0
	s_add_u32 m0, s28, 0xc000
	v_lshl_add_u64 v[164:165], v[138:139], 0, s[34:35]
	global_load_lds_dwordx4 v[164:165], off
	ds_read_b128 v[200:203], v0 offset:8192
	s_waitcnt lgkmcnt(5)
	v_mfma_f32_32x32x16_bf16 v[18:33], v[204:207], v[208:211], v[18:33]
	v_mfma_f32_32x32x16_bf16 v[2:17], v[204:207], v[212:215], v[2:17]
	s_add_u32 s34, s4, 0xe60080
	s_addc_u32 s35, s5, 0
	s_add_u32 m0, s28, 0xe000
	v_lshl_add_u64 v[164:165], v[138:139], 0, s[34:35]
	global_load_lds_dwordx4 v[164:165], off
	ds_read_b128 v[204:207], v0 offset:12288
	v_add3_u32 v191, s15, v151, v150
	v_add_u32_e32 v191, v191, v155
	v_add3_u32 v0, s15, v149, v150
	v_add_u32_e32 v0, v0, v155
	ds_read_b128 v[208:211], v191 offset:32768
	ds_read_b128 v[212:215], v191 offset:36864
	s_waitcnt lgkmcnt(5)
	v_mfma_f32_32x32x16_bf16 v[114:129], v[192:195], v[156:159], v[114:129]
	v_mfma_f32_32x32x16_bf16 v[98:113], v[192:195], v[160:163], v[98:113]
	ds_read_b128 v[192:195], v0
	s_waitcnt lgkmcnt(5)
	v_mfma_f32_32x32x16_bf16 v[82:97], v[196:199], v[156:159], v[82:97]
	v_mfma_f32_32x32x16_bf16 v[66:81], v[196:199], v[160:163], v[66:81]
	ds_read_b128 v[196:199], v0 offset:4096
	s_waitcnt lgkmcnt(5)
	v_mfma_f32_32x32x16_bf16 v[50:65], v[200:203], v[156:159], v[50:65]
	v_mfma_f32_32x32x16_bf16 v[34:49], v[200:203], v[160:163], v[34:49]
	ds_read_b128 v[200:203], v0 offset:8192
	s_waitcnt lgkmcnt(5)
	v_mfma_f32_32x32x16_bf16 v[18:33], v[204:207], v[156:159], v[18:33]
	v_mfma_f32_32x32x16_bf16 v[2:17], v[204:207], v[160:163], v[2:17]
	ds_read_b128 v[204:207], v0 offset:12288
	s_waitcnt lgkmcnt(3)
	v_mfma_f32_32x32x16_bf16 v[114:129], v[192:195], v[208:211], v[114:129]
	v_mfma_f32_32x32x16_bf16 v[98:113], v[192:195], v[212:215], v[98:113]
	s_waitcnt lgkmcnt(2)
	v_mfma_f32_32x32x16_bf16 v[82:97], v[196:199], v[208:211], v[82:97]
	v_mfma_f32_32x32x16_bf16 v[66:81], v[196:199], v[212:215], v[66:81]
	s_waitcnt lgkmcnt(0)
	s_waitcnt vmcnt(0)
	s_barrier
; template <int EPI, int AMAP, int KOFFMODE, int K>
; __device__ __forceinline__ void gemm_phase(unsigned char* smem, const bf16_t* A, int lda, const bf16_t* Bt, int NT, const EpiArgs& ea) {
;     ...
;             for (int s = 0; s < 4; ++s) {
;                 if (s < 3) {
;                     const int o_ = (((2 * (s + 1)) ^ yz) & 7) * 16;
;                     fb[(s + 1) & 1][0] = *(const bf16x8*)(Bc + o_);
;                     fb[(s + 1) & 1][1] = *(const bf16x8*)(Bc + 32 * 128 + o_);
; #pragma unroll
;                     for (int i = 0; i < 4; ++i) fa[(s + 1) & 1][i] = *(const bf16x8*)(Ac + i * 32 * 128 + o_);
;                 }
; #pragma unroll
;                 for (int i = 0; i < 4; ++i) {
;                     acc[i][0] = __builtin_amdgcn_mfma_f32_32x32x16_bf16(fa[s & 1][i], fb[s & 1][0], acc[i][0], 0, 0, 0);
;                     acc[i][1] = __builtin_amdgcn_mfma_f32_32x32x16_bf16(fa[s & 1][i], fb[s & 1][1], acc[i][1], 0, 0, 0);
;                 }
;                 __builtin_amdgcn_sched_barrier(0);
;             }
;             if (kt + 1 < nk) asm volatile("s_waitcnt vmcnt(0)" ::: "memory");
;             __builtin_amdgcn_s_barrier();
;             cur ^= 1;
	v_add3_u32 v191, s14, v151, v150
	v_add_u32_e32 v191, v191, v152
	v_add3_u32 v0, s14, v149, v150
	v_add_u32_e32 v0, v0, v152
	ds_read_b128 v[156:159], v191 offset:32768
	ds_read_b128 v[160:163], v191 offset:36864
	ds_read_b128 v[192:195], v0
	ds_read_b128 v[196:199], v0 offset:4096
	v_mfma_f32_32x32x16_bf16 v[50:65], v[200:203], v[208:211], v[50:65]
	v_mfma_f32_32x32x16_bf16 v[34:49], v[200:203], v[212:215], v[34:49]
	ds_read_b128 v[200:203], v0 offset:8192
	v_mfma_f32_32x32x16_bf16 v[18:33], v[204:207], v[208:211], v[18:33]
	v_mfma_f32_32x32x16_bf16 v[2:17], v[204:207], v[212:215], v[2:17]
	ds_read_b128 v[204:207], v0 offset:12288
	s_xor_b32 s15, s11, 1
	s_add_u32 s4, s4, 0x80
	s_addc_u32 s5, s5, 0
	s_cmpk_eq_i32 s4, 0x780
	s_cbranch_scc0 .LBB0_1032
	s_waitcnt lgkmcnt(0)
	s_andn2_b64 vcc, exec, s[2:3]
	s_lshl_b32 s2, s15, 16
	s_cbranch_vccnz .LBB0_1024
	v_add_u32_e32 v136, s10, v143
	s_xor_b32 s3, s2, 0x10000
	v_ashrrev_i32_e32 v137, 31, v136
	v_add_u32_e32 v138, s9, v143
	v_add_u32_e32 v0, s3, v144
	v_lshlrev_b64 v[136:137], 11, v[136:137]
	v_ashrrev_i32_e32 v139, 31, v138
	v_add_u32_e32 v156, 0x8000, v0
	v_readfirstlane_b32 s3, v0
	v_lshlrev_b64 v[138:139], 11, v[138:139]
	v_lshl_add_u64 v[136:137], v[130:131], 0, v[136:137]
	s_mov_b32 m0, s3
	v_readfirstlane_b32 s3, v156
	v_add_u32_e32 v158, 0x2000, v0
	v_lshl_add_u64 v[138:139], v[132:133], 0, v[138:139]
	global_load_lds_dwordx4 v[136:137], off
	s_mov_b32 m0, s3
	s_mov_b64 s[4:5], 0x20000
	v_readfirstlane_b32 s3, v158
	v_add_u32_e32 v158, 0xa000, v0
	global_load_lds_dwordx4 v[138:139], off
	v_lshl_add_u64 v[156:157], v[136:137], 0, s[4:5]
	s_mov_b32 m0, s3
	v_readfirstlane_b32 s3, v158
	v_add_u32_e32 v158, 0x4000, v0
	global_load_lds_dwordx4 v[156:157], off
	v_lshl_add_u64 v[156:157], v[138:139], 0, s[4:5]
	s_mov_b32 m0, s3
	s_mov_b64 s[4:5], 0x40000
	v_readfirstlane_b32 s3, v158
	v_add_u32_e32 v158, 0xc000, v0
	global_load_lds_dwordx4 v[156:157], off
	v_lshl_add_u64 v[156:157], v[136:137], 0, s[4:5]
	s_mov_b32 m0, s3
	v_readfirstlane_b32 s3, v158
	global_load_lds_dwordx4 v[156:157], off
	v_lshl_add_u64 v[156:157], v[138:139], 0, s[4:5]
	s_mov_b32 m0, s3
	s_mov_b64 s[4:5], 0x60000
	global_load_lds_dwordx4 v[156:157], off
	v_add_u32_e32 v156, 0x6000, v0
	v_add_u32_e32 v0, 0xe000, v0
	v_readfirstlane_b32 s3, v156
	v_lshl_add_u64 v[136:137], v[136:137], 0, s[4:5]
	s_mov_b32 m0, s3
	v_readfirstlane_b32 s3, v0
	global_load_lds_dwordx4 v[136:137], off
	v_lshl_add_u64 v[136:137], v[138:139], 0, s[4:5]
	s_mov_b32 m0, s3
	s_nop 0
	global_load_lds_dwordx4 v[136:137], off
	s_branch .LBB0_1024

; template <int EPI, int AMAP, int KOFFMODE, int K>
; __device__ __forceinline__ void gemm_phase(unsigned char* smem, const bf16_t* A, int lda, const bf16_t* Bt, int NT, const EpiArgs& ea) {
;     ...
;         for (int kt = 0; kt < nk; ++kt) {
;             if (kt + 1 < nk) GEMM_DMA(m0, n0, kt + 1, cur ^ 1);
;             else if (have_next) GEMM_DMA(m0n, n0n, 0, cur ^ 1);
;             const unsigned char* Ac = smem + cur * STGB + (wm * 128 + l31) * 128;
;             const unsigned char* Bc = smem + cur * STGB + 32768 + (wn * 64 + l31) * 128;
;             bf16x8 fa[2][4], fb[2][2];
;             fb[0][0] = *(const bf16x8*)(Bc + (((0) ^ yz) & 7) * 16);
;             fb[0][1] = *(const bf16x8*)(Bc + 32 * 128 + (((0) ^ yz) & 7) * 16);
; #pragma unroll
;             for (int i = 0; i < 4; ++i) fa[0][i] = *(const bf16x8*)(Ac + i * 32 * 128 + (((0) ^ yz) & 7) * 16);
; #pragma unroll
;             for (int s = 0; s < 4; ++s) {
;                 if (s < 3) {
;                     const int o_ = (((2 * (s + 1)) ^ yz) & 7) * 16;
;                     fb[(s + 1) & 1][0] = *(const bf16x8*)(Bc + o_);
;                     fb[(s + 1) & 1][1] = *(const bf16x8*)(Bc + 32 * 128 + o_);
; #pragma unroll
;                     for (int i = 0; i < 4; ++i) fa[(s + 1) & 1][i] = *(const bf16x8*)(Ac + i * 32 * 128 + o_);
;                 }
; #pragma unroll
;                 for (int i = 0; i < 4; ++i) {
;                     acc[i][0] = __builtin_amdgcn_mfma_f32_32x32x16_bf16(fa[s & 1][i], fb[s & 1][0], acc[i][0], 0, 0, 0);
;                     acc[i][1] = __builtin_amdgcn_mfma_f32_32x32x16_bf16(fa[s & 1][i], fb[s & 1][1], acc[i][1], 0, 0, 0);
;                 }
;                 __builtin_amdgcn_sched_barrier(0);
;             }
;             if (kt + 1 < nk) asm volatile("s_waitcnt vmcnt(0)" ::: "memory");
;             __builtin_amdgcn_s_barrier();
;             cur ^= 1;
;         }
.LBB0_1161:
	s_mov_b32 s13, s34
	s_lshl_b32 s36, s13, 16
	s_xor_b32 s28, s36, 0x10000
	v_readfirstlane_b32 vcc_lo, v144
	s_nop 0
	s_add_u32 vcc_lo, vcc_lo, s28
	v_add3_u32 v191, s36, v151, v150
	v_add_u32_e32 v191, v191, v153
	v_add3_u32 v0, s36, v149, v150
	v_add_u32_e32 v0, v0, v153
	ds_read_b128 v[208:211], v191 offset:32768
	ds_read_b128 v[212:215], v191 offset:36864
	s_waitcnt lgkmcnt(5)
	v_mfma_f32_32x32x16_bf16 v[114:129], v[192:195], v[156:159], v[114:129]
	s_add_u32 s34, s8, 0x4100080
	s_addc_u32 s35, s9, 0
	s_mov_b32 m0, vcc_lo
	v_lshl_add_u64 v[164:165], v[136:137], 0, s[34:35]
	global_load_lds_dwordx4 v[164:165], off
	v_mfma_f32_32x32x16_bf16 v[98:113], v[192:195], v[160:163], v[98:113]
	s_add_u32 s34, s8, 0x4158080
	s_addc_u32 s35, s9, 0
	s_add_u32 m0, vcc_lo, 0x2000
	v_lshl_add_u64 v[164:165], v[136:137], 0, s[34:35]
	global_load_lds_dwordx4 v[164:165], off
	ds_read_b128 v[192:195], v0
	s_waitcnt lgkmcnt(5)
	v_mfma_f32_32x32x16_bf16 v[82:97], v[196:199], v[156:159], v[82:97]
	s_add_u32 s34, s8, 0x41b0080
	s_addc_u32 s35, s9, 0
	s_add_u32 m0, vcc_lo, 0x4000
	v_lshl_add_u64 v[164:165], v[136:137], 0, s[34:35]
	global_load_lds_dwordx4 v[164:165], off
	v_mfma_f32_32x32x16_bf16 v[66:81], v[196:199], v[160:163], v[66:81]
	s_add_u32 s34, s8, 0x4208080
	s_addc_u32 s35, s9, 0
	s_add_u32 m0, vcc_lo, 0x6000
	v_lshl_add_u64 v[164:165], v[136:137], 0, s[34:35]
	global_load_lds_dwordx4 v[164:165], off
	ds_read_b128 v[196:199], v0 offset:4096
	s_waitcnt lgkmcnt(5)
	v_mfma_f32_32x32x16_bf16 v[50:65], v[200:203], v[156:159], v[50:65]
	v_mfma_f32_32x32x16_bf16 v[34:49], v[200:203], v[160:163], v[34:49]
	ds_read_b128 v[200:203], v0 offset:8192
	s_waitcnt lgkmcnt(5)
	v_mfma_f32_32x32x16_bf16 v[18:33], v[204:207], v[156:159], v[18:33]
	v_mfma_f32_32x32x16_bf16 v[2:17], v[204:207], v[160:163], v[2:17]
	ds_read_b128 v[204:207], v0 offset:12288
	v_add3_u32 v191, s36, v151, v150
	v_add_u32_e32 v191, v191, v154
	v_add3_u32 v0, s36, v149, v150
	v_add_u32_e32 v0, v0, v154
	ds_read_b128 v[156:159], v191 offset:32768
	ds_read_b128 v[160:163], v191 offset:36864
	s_waitcnt lgkmcnt(5)
	v_mfma_f32_32x32x16_bf16 v[114:129], v[192:195], v[208:211], v[114:129]
	v_mfma_f32_32x32x16_bf16 v[98:113], v[192:195], v[212:215], v[98:113]
	s_add_u32 s34, s8, 0x1900080
	s_addc_u32 s35, s9, 0
	s_add_u32 m0, vcc_lo, 0x8000
	v_lshl_add_u64 v[164:165], v[138:139], 0, s[34:35]
	global_load_lds_dwordx4 v[164:165], off
	ds_read_b128 v[192:195], v0
	s_waitcnt lgkmcnt(5)
	v_mfma_f32_32x32x16_bf16 v[82:97], v[196:199], v[208:211], v[82:97]
	v_mfma_f32_32x32x16_bf16 v[66:81], v[196:199], v[212:215], v[66:81]
	s_add_u32 s34, s8, 0x1958080
	s_addc_u32 s35, s9, 0
	s_add_u32 m0, vcc_lo, 0xa000
	v_lshl_add_u64 v[164:165], v[138:139], 0, s[34:35]
	global_load_lds_dwordx4 v[164:165], off
	ds_read_b128 v[196:199], v0 offset:4096
	s_waitcnt lgkmcnt(5)
	v_mfma_f32_32x32x16_bf16 v[50:65], v[200:203], v[208:211], v[50:65]
	v_mfma_f32_32x32x16_bf16 v[34:49], v[200:203], v[212:215], v[34:49]
	s_add_u32 s34, s8, 0x19b0080
	s_addc_u32 s35, s9, 0
	s_add_u32 m0, vcc_lo, 0xc000
	v_lshl_add_u64 v[164:165], v[138:139], 0, s[34:35]
	global_load_lds_dwordx4 v[164:165], off
	ds_read_b128 v[200:203], v0 offset:8192
	s_waitcnt lgkmcnt(5)
	v_mfma_f32_32x32x16_bf16 v[18:33], v[204:207], v[208:211], v[18:33]
	v_mfma_f32_32x32x16_bf16 v[2:17], v[204:207], v[212:215], v[2:17]
	s_add_u32 s34, s8, 0x1a08080
	s_addc_u32 s35, s9, 0
	s_add_u32 m0, vcc_lo, 0xe000
	v_lshl_add_u64 v[164:165], v[138:139], 0, s[34:35]
	global_load_lds_dwordx4 v[164:165], off
	ds_read_b128 v[204:207], v0 offset:12288
	v_add3_u32 v191, s36, v151, v150
	v_add_u32_e32 v191, v191, v155
	v_add3_u32 v0, s36, v149, v150
	v_add_u32_e32 v0, v0, v155
	ds_read_b128 v[208:211], v191 offset:32768
	ds_read_b128 v[212:215], v191 offset:36864
	s_waitcnt lgkmcnt(5)
	v_mfma_f32_32x32x16_bf16 v[114:129], v[192:195], v[156:159], v[114:129]
	v_mfma_f32_32x32x16_bf16 v[98:113], v[192:195], v[160:163], v[98:113]
	ds_read_b128 v[192:195], v0
	s_waitcnt lgkmcnt(5)
	v_mfma_f32_32x32x16_bf16 v[82:97], v[196:199], v[156:159], v[82:97]
	v_mfma_f32_32x32x16_bf16 v[66:81], v[196:199], v[160:163], v[66:81]
	ds_read_b128 v[196:199], v0 offset:4096
	s_waitcnt lgkmcnt(5)
	v_mfma_f32_32x32x16_bf16 v[50:65], v[200:203], v[156:159], v[50:65]
	v_mfma_f32_32x32x16_bf16 v[34:49], v[200:203], v[160:163], v[34:49]
	ds_read_b128 v[200:203], v0 offset:8192
	s_waitcnt lgkmcnt(5)
	v_mfma_f32_32x32x16_bf16 v[18:33], v[204:207], v[156:159], v[18:33]
	v_mfma_f32_32x32x16_bf16 v[2:17], v[204:207], v[160:163], v[2:17]
	ds_read_b128 v[204:207], v0 offset:12288
	s_waitcnt lgkmcnt(3)
	v_mfma_f32_32x32x16_bf16 v[114:129], v[192:195], v[208:211], v[114:129]
	v_mfma_f32_32x32x16_bf16 v[98:113], v[192:195], v[212:215], v[98:113]
	s_waitcnt lgkmcnt(2)
	v_mfma_f32_32x32x16_bf16 v[82:97], v[196:199], v[208:211], v[82:97]
	v_mfma_f32_32x32x16_bf16 v[66:81], v[196:199], v[212:215], v[66:81]
	s_waitcnt lgkmcnt(0)
	s_waitcnt vmcnt(0)
	s_barrier
; template <int EPI, int AMAP, int KOFFMODE, int K>
; __device__ __forceinline__ void gemm_phase(unsigned char* smem, const bf16_t* A, int lda, const bf16_t* Bt, int NT, const EpiArgs& ea) {
;     ...
;             for (int s = 0; s < 4; ++s) {
;                 if (s < 3) {
;                     const int o_ = (((2 * (s + 1)) ^ yz) & 7) * 16;
;                     fb[(s + 1) & 1][0] = *(const bf16x8*)(Bc + o_);
;                     fb[(s + 1) & 1][1] = *(const bf16x8*)(Bc + 32 * 128 + o_);
; #pragma unroll
;                     for (int i = 0; i < 4; ++i) fa[(s + 1) & 1][i] = *(const bf16x8*)(Ac + i * 32 * 128 + o_);
;                 }
; #pragma unroll
;                 for (int i = 0; i < 4; ++i) {
;                     acc[i][0] = __builtin_amdgcn_mfma_f32_32x32x16_bf16(fa[s & 1][i], fb[s & 1][0], acc[i][0], 0, 0, 0);
;                     acc[i][1] = __builtin_amdgcn_mfma_f32_32x32x16_bf16(fa[s & 1][i], fb[s & 1][1], acc[i][1], 0, 0, 0);
;                 }
;                 __builtin_amdgcn_sched_barrier(0);
;             }
;             if (kt + 1 < nk) asm volatile("s_waitcnt vmcnt(0)" ::: "memory");
;             __builtin_amdgcn_s_barrier();
;             cur ^= 1;
	v_add3_u32 v191, s28, v151, v150
	v_add_u32_e32 v191, v191, v152
	v_add3_u32 v0, s28, v149, v150
	v_add_u32_e32 v0, v0, v152
	ds_read_b128 v[156:159], v191 offset:32768
	ds_read_b128 v[160:163], v191 offset:36864
	ds_read_b128 v[192:195], v0
	ds_read_b128 v[196:199], v0 offset:4096
	v_mfma_f32_32x32x16_bf16 v[50:65], v[200:203], v[208:211], v[50:65]
	v_mfma_f32_32x32x16_bf16 v[34:49], v[200:203], v[212:215], v[34:49]
	ds_read_b128 v[200:203], v0 offset:8192
	v_mfma_f32_32x32x16_bf16 v[18:33], v[204:207], v[208:211], v[18:33]
	v_mfma_f32_32x32x16_bf16 v[2:17], v[204:207], v[212:215], v[2:17]
	ds_read_b128 v[204:207], v0 offset:12288
	s_xor_b32 s34, s13, 1
	s_add_u32 s8, s8, 0x80
	s_addc_u32 s9, s9, 0
	s_cmpk_eq_i32 s8, 0x1580
	s_cbranch_scc0 .LBB0_1161
	s_waitcnt lgkmcnt(0)
	s_andn2_b64 vcc, exec, s[2:3]
	s_lshl_b32 s2, s34, 16
	s_cbranch_vccnz .LBB0_1153
	v_add_u32_e32 v0, s12, v143
	v_add_u32_e32 v136, s11, v143
	s_movk_i32 s3, 0x1600
	v_mad_i64_i32 v[136:137], s[8:9], v136, s3, v[132:133]
	v_mad_i64_i32 v[138:139], s[8:9], v0, s3, v[130:131]
	s_xor_b32 s3, s2, 0x10000
	v_add_u32_e32 v0, s3, v144
	v_add_u32_e32 v156, 0x8000, v0
	v_readfirstlane_b32 s3, v0
	s_mov_b32 m0, s3
	v_readfirstlane_b32 s3, v156
	v_add_u32_e32 v158, 0x2000, v0
	global_load_lds_dwordx4 v[138:139], off
	s_mov_b32 m0, s3
	s_mov_b64 s[8:9], 0x58000
	v_readfirstlane_b32 s3, v158
	v_add_u32_e32 v158, 0xa000, v0
	global_load_lds_dwordx4 v[136:137], off
	v_lshl_add_u64 v[156:157], v[138:139], 0, s[8:9]
	s_mov_b32 m0, s3
	v_readfirstlane_b32 s3, v158
	v_add_u32_e32 v158, 0x4000, v0
	global_load_lds_dwordx4 v[156:157], off
	v_lshl_add_u64 v[156:157], v[136:137], 0, s[8:9]
	s_mov_b32 m0, s3
	s_mov_b64 s[8:9], 0xb0000
	v_readfirstlane_b32 s3, v158
	v_add_u32_e32 v158, 0xc000, v0
	global_load_lds_dwordx4 v[156:157], off
	v_lshl_add_u64 v[156:157], v[138:139], 0, s[8:9]
	s_mov_b32 m0, s3
	v_readfirstlane_b32 s3, v158
	global_load_lds_dwordx4 v[156:157], off
	v_lshl_add_u64 v[156:157], v[136:137], 0, s[8:9]
	s_mov_b32 m0, s3
	s_mov_b64 s[8:9], 0x108000
	global_load_lds_dwordx4 v[156:157], off
	v_add_u32_e32 v156, 0x6000, v0
	v_add_u32_e32 v0, 0xe000, v0
	v_readfirstlane_b32 s3, v156
	v_lshl_add_u64 v[138:139], v[138:139], 0, s[8:9]
	s_mov_b32 m0, s3
	v_readfirstlane_b32 s3, v0
	global_load_lds_dwordx4 v[138:139], off
	v_lshl_add_u64 v[136:137], v[136:137], 0, s[8:9]
	s_mov_b32 m0, s3
	s_nop 0
	global_load_lds_dwordx4 v[136:137], off
	s_branch .LBB0_1153

; template <int EPI, int AMAP, int KOFFMODE, int K>
; __device__ __forceinline__ void gemm_phase(unsigned char* smem, const bf16_t* A, int lda, const bf16_t* Bt, int NT, const EpiArgs& ea) {
;     ...
;         for (int kt = 0; kt < nk; ++kt) {
;             if (kt + 1 < nk) GEMM_DMA(m0, n0, kt + 1, cur ^ 1);
;             else if (have_next) GEMM_DMA(m0n, n0n, 0, cur ^ 1);
;             const unsigned char* Ac = smem + cur * STGB + (wm * 128 + l31) * 128;
;             const unsigned char* Bc = smem + cur * STGB + 32768 + (wn * 64 + l31) * 128;
;             bf16x8 fa[2][4], fb[2][2];
;             fb[0][0] = *(const bf16x8*)(Bc + (((0) ^ yz) & 7) * 16);
;             fb[0][1] = *(const bf16x8*)(Bc + 32 * 128 + (((0) ^ yz) & 7) * 16);
; #pragma unroll
;             for (int i = 0; i < 4; ++i) fa[0][i] = *(const bf16x8*)(Ac + i * 32 * 128 + (((0) ^ yz) & 7) * 16);
; #pragma unroll
;             for (int s = 0; s < 4; ++s) {
;                 if (s < 3) {
;                     const int o_ = (((2 * (s + 1)) ^ yz) & 7) * 16;
;                     fb[(s + 1) & 1][0] = *(const bf16x8*)(Bc + o_);
;                     fb[(s + 1) & 1][1] = *(const bf16x8*)(Bc + 32 * 128 + o_);
; #pragma unroll
;                     for (int i = 0; i < 4; ++i) fa[(s + 1) & 1][i] = *(const bf16x8*)(Ac + i * 32 * 128 + o_);
;                 }
; #pragma unroll
;                 for (int i = 0; i < 4; ++i) {
;                     acc[i][0] = __builtin_amdgcn_mfma_f32_32x32x16_bf16(fa[s & 1][i], fb[s & 1][0], acc[i][0], 0, 0, 0);
;                     acc[i][1] = __builtin_amdgcn_mfma_f32_32x32x16_bf16(fa[s & 1][i], fb[s & 1][1], acc[i][1], 0, 0, 0);
;                 }
;                 __builtin_amdgcn_sched_barrier(0);
;             }
;             if (kt + 1 < nk) asm volatile("s_waitcnt vmcnt(0)" ::: "memory");
;             __builtin_amdgcn_s_barrier();
;             cur ^= 1;
;         }
.LBB0_1429:
	s_mov_b32 s9, s13
	s_lshl_b32 s13, s9, 16
	s_xor_b32 s12, s13, 0x10000
	v_readfirstlane_b32 vcc_lo, v143
	s_nop 0
	s_add_u32 vcc_lo, vcc_lo, s12
	v_add3_u32 v155, s13, v150, v149
	v_add_u32_e32 v155, v155, v152
	v_add3_u32 v0, s13, v147, v149
	v_add_u32_e32 v0, v0, v152
	ds_read_b128 v[208:211], v155 offset:32768
	ds_read_b128 v[212:215], v155 offset:36864
	s_waitcnt lgkmcnt(5)
	v_mfma_f32_32x32x16_bf16 v[114:129], v[192:195], v[156:159], v[114:129]
	s_add_u32 s14, s4, 0xe380080
	s_addc_u32 s15, s5, 0
	s_mov_b32 m0, vcc_lo
	v_lshl_add_u64 v[164:165], v[136:137], 0, s[14:15]
	global_load_lds_dwordx4 v[164:165], off
	v_mfma_f32_32x32x16_bf16 v[98:113], v[192:195], v[160:163], v[98:113]
	s_add_u32 s14, s4, 0xe3a0080
	s_addc_u32 s15, s5, 0
	s_add_u32 m0, vcc_lo, 0x2000
	v_lshl_add_u64 v[164:165], v[136:137], 0, s[14:15]
	global_load_lds_dwordx4 v[164:165], off
	ds_read_b128 v[192:195], v0
	s_waitcnt lgkmcnt(5)
	v_mfma_f32_32x32x16_bf16 v[82:97], v[196:199], v[156:159], v[82:97]
	s_add_u32 s14, s4, 0xe3c0080
	s_addc_u32 s15, s5, 0
	s_add_u32 m0, vcc_lo, 0x4000
	v_lshl_add_u64 v[164:165], v[136:137], 0, s[14:15]
	global_load_lds_dwordx4 v[164:165], off
	v_mfma_f32_32x32x16_bf16 v[66:81], v[196:199], v[160:163], v[66:81]
	s_add_u32 s14, s4, 0xe3e0080
	s_addc_u32 s15, s5, 0
	s_add_u32 m0, vcc_lo, 0x6000
	v_lshl_add_u64 v[164:165], v[136:137], 0, s[14:15]
	global_load_lds_dwordx4 v[164:165], off
	ds_read_b128 v[196:199], v0 offset:4096
	s_waitcnt lgkmcnt(5)
	v_mfma_f32_32x32x16_bf16 v[50:65], v[200:203], v[156:159], v[50:65]
	v_mfma_f32_32x32x16_bf16 v[34:49], v[200:203], v[160:163], v[34:49]
	ds_read_b128 v[200:203], v0 offset:8192
	s_waitcnt lgkmcnt(5)
	v_mfma_f32_32x32x16_bf16 v[18:33], v[204:207], v[156:159], v[18:33]
	v_mfma_f32_32x32x16_bf16 v[2:17], v[204:207], v[160:163], v[2:17]
	ds_read_b128 v[204:207], v0 offset:12288
	v_add3_u32 v155, s13, v150, v149
	v_add_u32_e32 v155, v155, v153
	v_add3_u32 v0, s13, v147, v149
	v_add_u32_e32 v0, v0, v153
	ds_read_b128 v[156:159], v155 offset:32768
	ds_read_b128 v[160:163], v155 offset:36864
	s_waitcnt lgkmcnt(5)
	v_mfma_f32_32x32x16_bf16 v[114:129], v[192:195], v[208:211], v[114:129]
	v_mfma_f32_32x32x16_bf16 v[98:113], v[192:195], v[212:215], v[98:113]
	s_add_u32 s14, s4, s20
	s_addc_u32 s15, s5, s21
	s_add_u32 m0, vcc_lo, 0x8000
	v_lshl_add_u64 v[164:165], v[138:139], 0, s[14:15]
	global_load_lds_dwordx4 v[164:165], off
	ds_read_b128 v[192:195], v0
	s_waitcnt lgkmcnt(5)
	v_mfma_f32_32x32x16_bf16 v[82:97], v[196:199], v[208:211], v[82:97]
	v_mfma_f32_32x32x16_bf16 v[66:81], v[196:199], v[212:215], v[66:81]
	s_add_u32 s14, s4, 0x820080
	s_addc_u32 s15, s5, 0
	s_add_u32 m0, vcc_lo, 0xa000
	v_lshl_add_u64 v[164:165], v[138:139], 0, s[14:15]
	global_load_lds_dwordx4 v[164:165], off
	ds_read_b128 v[196:199], v0 offset:4096
	s_waitcnt lgkmcnt(5)
	v_mfma_f32_32x32x16_bf16 v[50:65], v[200:203], v[208:211], v[50:65]
	v_mfma_f32_32x32x16_bf16 v[34:49], v[200:203], v[212:215], v[34:49]
	s_add_u32 s14, s4, s68
	s_addc_u32 s15, s5, s69
	s_add_u32 m0, vcc_lo, 0xc000
	v_lshl_add_u64 v[164:165], v[138:139], 0, s[14:15]
	global_load_lds_dwordx4 v[164:165], off
	ds_read_b128 v[200:203], v0 offset:8192
	s_waitcnt lgkmcnt(5)
	v_mfma_f32_32x32x16_bf16 v[18:33], v[204:207], v[208:211], v[18:33]
	v_mfma_f32_32x32x16_bf16 v[2:17], v[204:207], v[212:215], v[2:17]
	s_add_u32 s14, s4, 0x860080
	s_addc_u32 s15, s5, 0
	s_add_u32 m0, vcc_lo, 0xe000
	v_lshl_add_u64 v[164:165], v[138:139], 0, s[14:15]
	global_load_lds_dwordx4 v[164:165], off
	ds_read_b128 v[204:207], v0 offset:12288
	v_add3_u32 v155, s13, v150, v149
	v_add_u32_e32 v155, v155, v154
	v_add3_u32 v0, s13, v147, v149
	v_add_u32_e32 v0, v0, v154
	ds_read_b128 v[208:211], v155 offset:32768
	ds_read_b128 v[212:215], v155 offset:36864
	s_waitcnt lgkmcnt(5)
	v_mfma_f32_32x32x16_bf16 v[114:129], v[192:195], v[156:159], v[114:129]
	v_mfma_f32_32x32x16_bf16 v[98:113], v[192:195], v[160:163], v[98:113]
	ds_read_b128 v[192:195], v0
	s_waitcnt lgkmcnt(5)
	v_mfma_f32_32x32x16_bf16 v[82:97], v[196:199], v[156:159], v[82:97]
	v_mfma_f32_32x32x16_bf16 v[66:81], v[196:199], v[160:163], v[66:81]
	ds_read_b128 v[196:199], v0 offset:4096
	s_waitcnt lgkmcnt(5)
	v_mfma_f32_32x32x16_bf16 v[50:65], v[200:203], v[156:159], v[50:65]
	v_mfma_f32_32x32x16_bf16 v[34:49], v[200:203], v[160:163], v[34:49]
	ds_read_b128 v[200:203], v0 offset:8192
	s_waitcnt lgkmcnt(5)
	v_mfma_f32_32x32x16_bf16 v[18:33], v[204:207], v[156:159], v[18:33]
	v_mfma_f32_32x32x16_bf16 v[2:17], v[204:207], v[160:163], v[2:17]
	ds_read_b128 v[204:207], v0 offset:12288
	s_waitcnt lgkmcnt(3)
	v_mfma_f32_32x32x16_bf16 v[114:129], v[192:195], v[208:211], v[114:129]
	v_mfma_f32_32x32x16_bf16 v[98:113], v[192:195], v[212:215], v[98:113]
	s_waitcnt lgkmcnt(2)
	v_mfma_f32_32x32x16_bf16 v[82:97], v[196:199], v[208:211], v[82:97]
	v_mfma_f32_32x32x16_bf16 v[66:81], v[196:199], v[212:215], v[66:81]
	s_waitcnt lgkmcnt(0)
	s_waitcnt vmcnt(0)
	s_barrier
; template <int EPI, int AMAP, int KOFFMODE, int K>
; __device__ __forceinline__ void gemm_phase(unsigned char* smem, const bf16_t* A, int lda, const bf16_t* Bt, int NT, const EpiArgs& ea) {
;     ...
;             for (int s = 0; s < 4; ++s) {
;                 if (s < 3) {
;                     const int o_ = (((2 * (s + 1)) ^ yz) & 7) * 16;
;                     fb[(s + 1) & 1][0] = *(const bf16x8*)(Bc + o_);
;                     fb[(s + 1) & 1][1] = *(const bf16x8*)(Bc + 32 * 128 + o_);
; #pragma unroll
;                     for (int i = 0; i < 4; ++i) fa[(s + 1) & 1][i] = *(const bf16x8*)(Ac + i * 32 * 128 + o_);
;                 }
; #pragma unroll
;                 for (int i = 0; i < 4; ++i) {
;                     acc[i][0] = __builtin_amdgcn_mfma_f32_32x32x16_bf16(fa[s & 1][i], fb[s & 1][0], acc[i][0], 0, 0, 0);
;                     acc[i][1] = __builtin_amdgcn_mfma_f32_32x32x16_bf16(fa[s & 1][i], fb[s & 1][1], acc[i][1], 0, 0, 0);
;                 }
;                 __builtin_amdgcn_sched_barrier(0);
;             }
;             if (kt + 1 < nk) asm volatile("s_waitcnt vmcnt(0)" ::: "memory");
;             __builtin_amdgcn_s_barrier();
;             cur ^= 1;
	v_add3_u32 v155, s12, v150, v149
	v_add_u32_e32 v155, v155, v151
	v_add3_u32 v0, s12, v147, v149
	v_add_u32_e32 v0, v0, v151
	ds_read_b128 v[156:159], v155 offset:32768
	ds_read_b128 v[160:163], v155 offset:36864
	ds_read_b128 v[192:195], v0
	ds_read_b128 v[196:199], v0 offset:4096
	v_mfma_f32_32x32x16_bf16 v[50:65], v[200:203], v[208:211], v[50:65]
	v_mfma_f32_32x32x16_bf16 v[34:49], v[200:203], v[212:215], v[34:49]
	ds_read_b128 v[200:203], v0 offset:8192
	v_mfma_f32_32x32x16_bf16 v[18:33], v[204:207], v[208:211], v[18:33]
	v_mfma_f32_32x32x16_bf16 v[2:17], v[204:207], v[212:215], v[2:17]
	ds_read_b128 v[204:207], v0 offset:12288
	s_xor_b32 s13, s9, 1
	s_add_u32 s4, s4, 0x80
	s_addc_u32 s5, s5, 0
	s_cmpk_eq_i32 s4, 0x780
	s_cbranch_scc0 .LBB0_1429
	s_waitcnt lgkmcnt(0)
	s_andn2_b64 vcc, exec, s[2:3]
	s_lshl_b32 s2, s13, 16
	s_cbranch_vccnz .LBB0_1421
	v_add_u32_e32 v136, s8, v142
	s_xor_b32 s3, s2, 0x10000
	v_ashrrev_i32_e32 v137, 31, v136
	v_add_u32_e32 v138, s7, v142
	v_add_u32_e32 v0, s3, v143
	v_lshlrev_b64 v[136:137], 11, v[136:137]
	v_ashrrev_i32_e32 v139, 31, v138
	v_add_u32_e32 v155, 0x8000, v0
	v_readfirstlane_b32 s3, v0
	v_lshlrev_b64 v[138:139], 11, v[138:139]
	v_lshl_add_u64 v[136:137], v[130:131], 0, v[136:137]
	s_mov_b32 m0, s3
	v_readfirstlane_b32 s3, v155
	v_add_u32_e32 v155, 0x2000, v0
	v_lshl_add_u64 v[138:139], v[132:133], 0, v[138:139]
	global_load_lds_dwordx4 v[136:137], off
	s_mov_b32 m0, s3
	s_mov_b64 s[4:5], 0x20000
	v_readfirstlane_b32 s3, v155
	v_add_u32_e32 v155, 0xa000, v0
	global_load_lds_dwordx4 v[138:139], off
	v_lshl_add_u64 v[156:157], v[136:137], 0, s[4:5]
	s_mov_b32 m0, s3
	v_readfirstlane_b32 s3, v155
	v_add_u32_e32 v155, 0x4000, v0
	global_load_lds_dwordx4 v[156:157], off
	v_lshl_add_u64 v[156:157], v[138:139], 0, s[4:5]
	s_mov_b32 m0, s3
	s_mov_b64 s[4:5], 0x40000
	v_readfirstlane_b32 s3, v155
	v_add_u32_e32 v155, 0xc000, v0
	global_load_lds_dwordx4 v[156:157], off
	v_lshl_add_u64 v[156:157], v[136:137], 0, s[4:5]
	s_mov_b32 m0, s3
	v_readfirstlane_b32 s3, v155
	v_add_u32_e32 v155, 0x6000, v0
	global_load_lds_dwordx4 v[156:157], off
	v_lshl_add_u64 v[156:157], v[138:139], 0, s[4:5]
	s_mov_b32 m0, s3
	s_mov_b64 s[4:5], 0x60000
	v_readfirstlane_b32 s3, v155
	v_add_u32_e32 v0, 0xe000, v0
	global_load_lds_dwordx4 v[156:157], off
	v_lshl_add_u64 v[136:137], v[136:137], 0, s[4:5]
	s_mov_b32 m0, s3
	v_readfirstlane_b32 s3, v0
	global_load_lds_dwordx4 v[136:137], off
	v_lshl_add_u64 v[136:137], v[138:139], 0, s[4:5]
	s_mov_b32 m0, s3
	s_nop 0
	global_load_lds_dwordx4 v[136:137], off
	s_branch .LBB0_1421
